# gemm_big fused loop: LDS barrier moved one MFMA pair earlier (18 MFMAs before, 14 after with writes+loads interleaved)
# speedup vs baseline: 1.0539x; 1.0029x over previous
; __device__ __forceinline__ void lds_barrier() { asm volatile("s_waitcnt lgkmcnt(0)\n\ts_barrier" ::: "memory"); }
; __device__ __forceinline__ f32x16 mfma32(bf16x8 a, bf16x8 b, f32x16 c) { return __builtin_amdgcn_mfma_f32_32x32x16_bf16(a, b, c, 0, 0, 0); }
; __device__ __forceinline__ void gemm_big(const bf16_t* __restrict__ A, long lda, const bf16_t* __restrict__ Bt, int K, f32x16 (&acc)[2][4], unsigned char* lds) {
;     ...
;     for (int kc = 0; kc < nk; ++kc) {
;         bf16x8 af[2][2], bfr[2][4];
;         af[0][0] = *(const bf16x8*)(Ac); af[0][1] = *(const bf16x8*)(Ac + 32 * GLD);
; #pragma unroll
;         for (int ni = 0; ni < 4; ++ni) bfr[0][ni] = *(const bf16x8*)(Bc + ni * 32 * GLD);
;         __builtin_amdgcn_s_setprio(3);
; #pragma unroll
;         for (int ks = 0; ks < 4; ++ks) {
;             const int cb = ks & 1, nb = cb ^ 1;
;             if (ks < 3) {
;                 af[nb][0] = *(const bf16x8*)(Ac + (ks + 1) * 16); af[nb][1] = *(const bf16x8*)(Ac + 32 * GLD + (ks + 1) * 16);
; #pragma unroll
;                 for (int ni = 0; ni < 4; ++ni) bfr[nb][ni] = *(const bf16x8*)(Bc + ni * 32 * GLD + (ks + 1) * 16);
;             }
;             __builtin_amdgcn_sched_barrier(0);
; #pragma unroll
;             for (int ni = 0; ni < 4; ++ni) { acc[0][ni] = mfma32(af[cb][0], bfr[cb][ni], acc[0][ni]); acc[1][ni] = mfma32(af[cb][1], bfr[cb][ni], acc[1][ni]); }
;             __builtin_amdgcn_sched_barrier(0);
;         }
;         __builtin_amdgcn_s_setprio(0);
;         lds_barrier();
;         if (kc + 1 < nk) {
;             lstore();
;             if (kc + 2 < nk) gload(kc + 2);
;             lds_barrier();
;         }
.LBB0_56:
	s_cmp_gt_u32 s13, 42
	s_cbranch_scc1 .Lmy_gorig_8
	ds_read_b128 v[190:193], v187
	ds_read_b128 v[194:197], v187 offset:4608
	ds_read_b128 v[198:201], v188 offset:18432
	ds_read_b128 v[202:205], v188 offset:23040
	ds_read_b128 v[206:209], v188 offset:27648
	ds_read_b128 v[210:213], v188 offset:32256
	s_setprio 3
	ds_read_b128 v[214:217], v187 offset:32
	ds_read_b128 v[218:221], v187 offset:4640
	ds_read_b128 v[224:227], v188 offset:18464
	ds_read_b128 v[234:237], v188 offset:23072
	ds_read_b128 v[238:241], v188 offset:27680
	ds_read_b128 v[242:245], v188 offset:32288
	s_waitcnt lgkmcnt(9)
	v_mfma_f32_32x32x16_bf16 v[114:129], v[190:193], v[198:201], v[114:129]
	v_mfma_f32_32x32x16_bf16 v[50:65], v[194:197], v[198:201], v[50:65]
	s_waitcnt lgkmcnt(8)
	v_mfma_f32_32x32x16_bf16 v[98:113], v[190:193], v[202:205], v[98:113]
	v_mfma_f32_32x32x16_bf16 v[34:49], v[194:197], v[202:205], v[34:49]
	s_waitcnt lgkmcnt(7)
	v_mfma_f32_32x32x16_bf16 v[82:97], v[190:193], v[206:209], v[82:97]
	v_mfma_f32_32x32x16_bf16 v[18:33], v[194:197], v[206:209], v[18:33]
	s_waitcnt lgkmcnt(6)
	v_mfma_f32_32x32x16_bf16 v[66:81], v[190:193], v[210:213], v[66:81]
	v_mfma_f32_32x32x16_bf16 v[2:17], v[194:197], v[210:213], v[2:17]
	ds_read_b128 v[190:193], v187 offset:64
	ds_read_b128 v[194:197], v187 offset:4672
	ds_read_b128 v[198:201], v188 offset:18496
	ds_read_b128 v[202:205], v188 offset:23104
	ds_read_b128 v[206:209], v188 offset:27712
	ds_read_b128 v[210:213], v188 offset:32320
	s_waitcnt lgkmcnt(9)
	v_mfma_f32_32x32x16_bf16 v[114:129], v[214:217], v[224:227], v[114:129]
	v_mfma_f32_32x32x16_bf16 v[50:65], v[218:221], v[224:227], v[50:65]
	s_waitcnt lgkmcnt(8)
	v_mfma_f32_32x32x16_bf16 v[98:113], v[214:217], v[234:237], v[98:113]
	v_mfma_f32_32x32x16_bf16 v[34:49], v[218:221], v[234:237], v[34:49]
	s_waitcnt lgkmcnt(7)
	v_mfma_f32_32x32x16_bf16 v[82:97], v[214:217], v[238:241], v[82:97]
	v_mfma_f32_32x32x16_bf16 v[18:33], v[218:221], v[238:241], v[18:33]
	s_waitcnt lgkmcnt(6)
	v_mfma_f32_32x32x16_bf16 v[66:81], v[214:217], v[242:245], v[66:81]
	v_mfma_f32_32x32x16_bf16 v[2:17], v[218:221], v[242:245], v[2:17]
	ds_read_b128 v[214:217], v187 offset:96
	ds_read_b128 v[218:221], v187 offset:4704
	ds_read_b128 v[224:227], v188 offset:18528
	ds_read_b128 v[234:237], v188 offset:23136
	ds_read_b128 v[238:241], v188 offset:27744
	ds_read_b128 v[242:245], v188 offset:32352
	s_waitcnt lgkmcnt(9)
	v_mfma_f32_32x32x16_bf16 v[114:129], v[190:193], v[198:201], v[114:129]
	v_mfma_f32_32x32x16_bf16 v[50:65], v[194:197], v[198:201], v[50:65]
	s_waitcnt lgkmcnt(0)
	s_barrier
	s_cmpk_eq_i32 s4, 0x1500
	s_cbranch_scc1 .Lmy_gB_8
	v_mfma_f32_32x32x16_bf16 v[98:113], v[190:193], v[202:205], v[98:113]
	s_waitcnt vmcnt(9)
	ds_write_b128 v189, v[130:133]
	v_mfma_f32_32x32x16_bf16 v[34:49], v[194:197], v[202:205], v[34:49]
	ds_write_b128 v189, v[134:137] offset:4608
	v_mfma_f32_32x32x16_bf16 v[82:97], v[190:193], v[206:209], v[82:97]
	ds_write_b128 v189, v[138:141] offset:9216
	s_add_u32 vcc_lo, s4, 0x78a8000
	s_addc_u32 vcc_hi, s5, 0
	s_nop 0
	v_lshl_add_u64 v[130:131], v[184:185], 0, vcc
	global_load_dwordx4 v[130:133], v[130:131], off offset:256
	v_mfma_f32_32x32x16_bf16 v[18:33], v[194:197], v[206:209], v[18:33]
	s_waitcnt vmcnt(8)
	ds_write_b128 v189, v[142:145] offset:13824
	s_add_u32 vcc_lo, s4, 0x78d4000
	s_addc_u32 vcc_hi, s5, 0
	s_nop 0
	v_lshl_add_u64 v[134:135], v[184:185], 0, vcc
	global_load_dwordx4 v[134:137], v[134:135], off offset:256
	v_mfma_f32_32x32x16_bf16 v[66:81], v[190:193], v[210:213], v[66:81]
	ds_write_b128 v189, v[146:149] offset:18432
	s_add_u32 vcc_lo, s4, 0x7900000
	s_addc_u32 vcc_hi, s5, 0
	s_nop 0
	v_lshl_add_u64 v[138:139], v[184:185], 0, vcc
	global_load_dwordx4 v[138:141], v[138:139], off offset:256
	v_mfma_f32_32x32x16_bf16 v[2:17], v[194:197], v[210:213], v[2:17]
	s_waitcnt vmcnt(9)
	ds_write_b128 v189, v[150:153] offset:23040
	s_add_u32 vcc_lo, s4, 0x792c000
	s_addc_u32 vcc_hi, s5, 0
	s_nop 0
	v_lshl_add_u64 v[142:143], v[184:185], 0, vcc
	global_load_dwordx4 v[142:145], v[142:143], off offset:256
	v_mfma_f32_32x32x16_bf16 v[114:129], v[214:217], v[224:227], v[114:129]
	s_waitcnt vmcnt(9)
	ds_write_b128 v189, v[154:157] offset:27648
	s_add_u32 vcc_lo, s4, 0x3328000
	s_addc_u32 vcc_hi, s5, 0
	s_nop 0
	v_lshl_add_u64 v[146:147], v[182:183], 0, vcc
	global_load_dwordx4 v[146:149], v[146:147], off offset:256
	v_mfma_f32_32x32x16_bf16 v[50:65], v[218:221], v[224:227], v[50:65]
	s_waitcnt vmcnt(9)
	ds_write_b128 v189, v[158:161] offset:32256
	s_add_u32 vcc_lo, s4, 0x3354000
	s_addc_u32 vcc_hi, s5, 0
	s_nop 0
	v_lshl_add_u64 v[150:151], v[182:183], 0, vcc
	global_load_dwordx4 v[150:153], v[150:151], off offset:256
	v_mfma_f32_32x32x16_bf16 v[98:113], v[214:217], v[234:237], v[98:113]
	s_waitcnt vmcnt(9)
	ds_write_b128 v189, v[162:165] offset:36864
	s_add_u32 vcc_lo, s4, 0x3380000
	s_addc_u32 vcc_hi, s5, 0
	s_nop 0
	v_lshl_add_u64 v[154:155], v[182:183], 0, vcc
	global_load_dwordx4 v[154:157], v[154:155], off offset:256
	v_mfma_f32_32x32x16_bf16 v[34:49], v[218:221], v[234:237], v[34:49]
	s_waitcnt vmcnt(9)
	ds_write_b128 v189, v[166:169] offset:41472
	s_add_u32 vcc_lo, s4, 0x33ac000
	s_addc_u32 vcc_hi, s5, 0
	s_nop 0
	v_lshl_add_u64 v[158:159], v[182:183], 0, vcc
	global_load_dwordx4 v[158:161], v[158:159], off offset:256
	v_mfma_f32_32x32x16_bf16 v[82:97], v[214:217], v[238:241], v[82:97]
	s_waitcnt vmcnt(9)
	ds_write_b128 v189, v[170:173] offset:46080
	s_add_u32 vcc_lo, s4, 0x33d8000
	s_addc_u32 vcc_hi, s5, 0
	s_nop 0
	v_lshl_add_u64 v[162:163], v[182:183], 0, vcc
	global_load_dwordx4 v[162:165], v[162:163], off offset:256
	v_mfma_f32_32x32x16_bf16 v[18:33], v[218:221], v[238:241], v[18:33]
	s_waitcnt vmcnt(9)
	ds_write_b128 v189, v[174:177] offset:50688
	s_add_u32 vcc_lo, s4, 0x3404000
	s_addc_u32 vcc_hi, s5, 0
	s_nop 0
	v_lshl_add_u64 v[166:167], v[182:183], 0, vcc
	global_load_dwordx4 v[166:169], v[166:167], off offset:256
	v_mfma_f32_32x32x16_bf16 v[66:81], v[214:217], v[242:245], v[66:81]
	s_add_u32 vcc_lo, s4, 0x3430000
	s_addc_u32 vcc_hi, s5, 0
	s_nop 0
	v_lshl_add_u64 v[170:171], v[182:183], 0, vcc
	global_load_dwordx4 v[170:173], v[170:171], off offset:256
	v_mfma_f32_32x32x16_bf16 v[2:17], v[218:221], v[242:245], v[2:17]
	s_add_u32 vcc_lo, s4, 0x345c000
	s_addc_u32 vcc_hi, s5, 0
	s_nop 0
	v_lshl_add_u64 v[174:175], v[182:183], 0, vcc
	global_load_dwordx4 v[174:177], v[174:175], off offset:256
	s_setprio 0
	s_branch .LBB0_54
; __device__ __forceinline__ void lds_barrier() { asm volatile("s_waitcnt lgkmcnt(0)\n\ts_barrier" ::: "memory"); }
; __device__ __forceinline__ f32x16 mfma32(bf16x8 a, bf16x8 b, f32x16 c) { return __builtin_amdgcn_mfma_f32_32x32x16_bf16(a, b, c, 0, 0, 0); }
; __device__ __forceinline__ void gemm_big(const bf16_t* __restrict__ A, long lda, const bf16_t* __restrict__ Bt, int K, f32x16 (&acc)[2][4], unsigned char* lds) {
;     ...
;             if (ks < 3) {
;                 af[nb][0] = *(const bf16x8*)(Ac + (ks + 1) * 16); af[nb][1] = *(const bf16x8*)(Ac + 32 * GLD + (ks + 1) * 16);
; #pragma unroll
;                 for (int ni = 0; ni < 4; ++ni) bfr[nb][ni] = *(const bf16x8*)(Bc + ni * 32 * GLD + (ks + 1) * 16);
;             }
;             __builtin_amdgcn_sched_barrier(0);
; #pragma unroll
;             for (int ni = 0; ni < 4; ++ni) { acc[0][ni] = mfma32(af[cb][0], bfr[cb][ni], acc[0][ni]); acc[1][ni] = mfma32(af[cb][1], bfr[cb][ni], acc[1][ni]); }
;             __builtin_amdgcn_sched_barrier(0);
;         }
;         __builtin_amdgcn_s_setprio(0);
;         lds_barrier();
;         if (kc + 1 < nk) {
;             lstore();
;             if (kc + 2 < nk) gload(kc + 2);
;             lds_barrier();
;         }
.Lmy_gB_8:
	v_mfma_f32_32x32x16_bf16 v[98:113], v[190:193], v[202:205], v[98:113]
	s_waitcnt vmcnt(9)
	ds_write_b128 v189, v[130:133]
	v_mfma_f32_32x32x16_bf16 v[34:49], v[194:197], v[202:205], v[34:49]
	ds_write_b128 v189, v[134:137] offset:4608
	v_mfma_f32_32x32x16_bf16 v[82:97], v[190:193], v[206:209], v[82:97]
	ds_write_b128 v189, v[138:141] offset:9216
	v_mfma_f32_32x32x16_bf16 v[18:33], v[194:197], v[206:209], v[18:33]
	s_waitcnt vmcnt(7)
	ds_write_b128 v189, v[142:145] offset:13824
	v_mfma_f32_32x32x16_bf16 v[66:81], v[190:193], v[210:213], v[66:81]
	ds_write_b128 v189, v[146:149] offset:18432
	v_mfma_f32_32x32x16_bf16 v[2:17], v[194:197], v[210:213], v[2:17]
	s_waitcnt vmcnt(6)
	ds_write_b128 v189, v[150:153] offset:23040
	v_mfma_f32_32x32x16_bf16 v[114:129], v[214:217], v[224:227], v[114:129]
	s_waitcnt vmcnt(5)
	ds_write_b128 v189, v[154:157] offset:27648
	v_mfma_f32_32x32x16_bf16 v[50:65], v[218:221], v[224:227], v[50:65]
	s_waitcnt vmcnt(4)
	ds_write_b128 v189, v[158:161] offset:32256
	v_mfma_f32_32x32x16_bf16 v[98:113], v[214:217], v[234:237], v[98:113]
	s_waitcnt vmcnt(3)
	ds_write_b128 v189, v[162:165] offset:36864
	v_mfma_f32_32x32x16_bf16 v[34:49], v[218:221], v[234:237], v[34:49]
	s_waitcnt vmcnt(2)
	ds_write_b128 v189, v[166:169] offset:41472
	v_mfma_f32_32x32x16_bf16 v[82:97], v[214:217], v[238:241], v[82:97]
	s_waitcnt vmcnt(1)
	ds_write_b128 v189, v[170:173] offset:46080
	v_mfma_f32_32x32x16_bf16 v[18:33], v[218:221], v[238:241], v[18:33]
	s_waitcnt vmcnt(0)
	ds_write_b128 v189, v[174:177] offset:50688
	v_mfma_f32_32x32x16_bf16 v[66:81], v[214:217], v[242:245], v[66:81]
	v_mfma_f32_32x32x16_bf16 v[2:17], v[218:221], v[242:245], v[2:17]
	s_setprio 0
	s_branch .LBB0_54

; __device__ __forceinline__ void lds_barrier() { asm volatile("s_waitcnt lgkmcnt(0)\n\ts_barrier" ::: "memory"); }
; __device__ __forceinline__ f32x16 mfma32(bf16x8 a, bf16x8 b, f32x16 c) { return __builtin_amdgcn_mfma_f32_32x32x16_bf16(a, b, c, 0, 0, 0); }
; __device__ __forceinline__ void gemm_big(const bf16_t* __restrict__ A, long lda, const bf16_t* __restrict__ Bt, int K, f32x16 (&acc)[2][4], unsigned char* lds) {
;     ...
;     for (int kc = 0; kc < nk; ++kc) {
;         bf16x8 af[2][2], bfr[2][4];
;         af[0][0] = *(const bf16x8*)(Ac); af[0][1] = *(const bf16x8*)(Ac + 32 * GLD);
; #pragma unroll
;         for (int ni = 0; ni < 4; ++ni) bfr[0][ni] = *(const bf16x8*)(Bc + ni * 32 * GLD);
;         __builtin_amdgcn_s_setprio(3);
; #pragma unroll
;         for (int ks = 0; ks < 4; ++ks) {
;             const int cb = ks & 1, nb = cb ^ 1;
;             if (ks < 3) {
;                 af[nb][0] = *(const bf16x8*)(Ac + (ks + 1) * 16); af[nb][1] = *(const bf16x8*)(Ac + 32 * GLD + (ks + 1) * 16);
; #pragma unroll
;                 for (int ni = 0; ni < 4; ++ni) bfr[nb][ni] = *(const bf16x8*)(Bc + ni * 32 * GLD + (ks + 1) * 16);
;             }
;             __builtin_amdgcn_sched_barrier(0);
; #pragma unroll
;             for (int ni = 0; ni < 4; ++ni) { acc[0][ni] = mfma32(af[cb][0], bfr[cb][ni], acc[0][ni]); acc[1][ni] = mfma32(af[cb][1], bfr[cb][ni], acc[1][ni]); }
;             __builtin_amdgcn_sched_barrier(0);
;         }
;         __builtin_amdgcn_s_setprio(0);
;         lds_barrier();
;         if (kc + 1 < nk) {
;             lstore();
;             if (kc + 2 < nk) gload(kc + 2);
;             lds_barrier();
;         }
.LBB0_67:
	s_cmp_gt_u32 s5, 14
	s_cbranch_scc1 .Lmy_gorig_7
	ds_read_b128 v[190:193], v187
	ds_read_b128 v[194:197], v187 offset:4608
	ds_read_b128 v[198:201], v188 offset:18432
	ds_read_b128 v[202:205], v188 offset:23040
	ds_read_b128 v[206:209], v188 offset:27648
	ds_read_b128 v[210:213], v188 offset:32256
	s_setprio 3
	ds_read_b128 v[214:217], v187 offset:32
	ds_read_b128 v[218:221], v187 offset:4640
	ds_read_b128 v[224:227], v188 offset:18464
	ds_read_b128 v[234:237], v188 offset:23072
	ds_read_b128 v[238:241], v188 offset:27680
	ds_read_b128 v[242:245], v188 offset:32288
	s_waitcnt lgkmcnt(9)
	v_mfma_f32_32x32x16_bf16 v[114:129], v[190:193], v[198:201], v[114:129]
	v_mfma_f32_32x32x16_bf16 v[82:97], v[194:197], v[198:201], v[82:97]
	s_waitcnt lgkmcnt(8)
	v_mfma_f32_32x32x16_bf16 v[98:113], v[190:193], v[202:205], v[98:113]
	v_mfma_f32_32x32x16_bf16 v[66:81], v[194:197], v[202:205], v[66:81]
	s_waitcnt lgkmcnt(7)
	v_mfma_f32_32x32x16_bf16 v[50:65], v[190:193], v[206:209], v[50:65]
	v_mfma_f32_32x32x16_bf16 v[18:33], v[194:197], v[206:209], v[18:33]
	s_waitcnt lgkmcnt(6)
	v_mfma_f32_32x32x16_bf16 v[34:49], v[190:193], v[210:213], v[34:49]
	v_mfma_f32_32x32x16_bf16 v[2:17], v[194:197], v[210:213], v[2:17]
	ds_read_b128 v[190:193], v187 offset:64
	ds_read_b128 v[194:197], v187 offset:4672
	ds_read_b128 v[198:201], v188 offset:18496
	ds_read_b128 v[202:205], v188 offset:23104
	ds_read_b128 v[206:209], v188 offset:27712
	ds_read_b128 v[210:213], v188 offset:32320
	s_waitcnt lgkmcnt(9)
	v_mfma_f32_32x32x16_bf16 v[114:129], v[214:217], v[224:227], v[114:129]
	v_mfma_f32_32x32x16_bf16 v[82:97], v[218:221], v[224:227], v[82:97]
	s_waitcnt lgkmcnt(8)
	v_mfma_f32_32x32x16_bf16 v[98:113], v[214:217], v[234:237], v[98:113]
	v_mfma_f32_32x32x16_bf16 v[66:81], v[218:221], v[234:237], v[66:81]
	s_waitcnt lgkmcnt(7)
	v_mfma_f32_32x32x16_bf16 v[50:65], v[214:217], v[238:241], v[50:65]
	v_mfma_f32_32x32x16_bf16 v[18:33], v[218:221], v[238:241], v[18:33]
	s_waitcnt lgkmcnt(6)
	v_mfma_f32_32x32x16_bf16 v[34:49], v[214:217], v[242:245], v[34:49]
	v_mfma_f32_32x32x16_bf16 v[2:17], v[218:221], v[242:245], v[2:17]
	ds_read_b128 v[214:217], v187 offset:96
	ds_read_b128 v[218:221], v187 offset:4704
	ds_read_b128 v[224:227], v188 offset:18528
	ds_read_b128 v[234:237], v188 offset:23136
	ds_read_b128 v[238:241], v188 offset:27744
	ds_read_b128 v[242:245], v188 offset:32352
	s_waitcnt lgkmcnt(9)
	v_mfma_f32_32x32x16_bf16 v[114:129], v[190:193], v[198:201], v[114:129]
	v_mfma_f32_32x32x16_bf16 v[82:97], v[194:197], v[198:201], v[82:97]
	s_waitcnt lgkmcnt(0)
	s_barrier
	s_cmpk_eq_i32 s6, 0x700
	s_cbranch_scc1 .Lmy_gB_7
	v_mfma_f32_32x32x16_bf16 v[98:113], v[190:193], v[202:205], v[98:113]
	s_waitcnt vmcnt(9)
	ds_write_b128 v189, v[130:133]
	v_mfma_f32_32x32x16_bf16 v[66:81], v[194:197], v[202:205], v[66:81]
	ds_write_b128 v189, v[134:137] offset:4608
	v_mfma_f32_32x32x16_bf16 v[50:65], v[190:193], v[206:209], v[50:65]
	ds_write_b128 v189, v[138:141] offset:9216
	s_add_u32 vcc_lo, s6, 0x38a8000
	s_addc_u32 vcc_hi, s7, 0
	s_nop 0
	v_lshl_add_u64 v[130:131], v[184:185], 0, vcc
	global_load_dwordx4 v[130:133], v[130:131], off offset:256
	v_mfma_f32_32x32x16_bf16 v[18:33], v[194:197], v[206:209], v[18:33]
	s_waitcnt vmcnt(8)
	ds_write_b128 v189, v[142:145] offset:13824
	s_add_u32 vcc_lo, s6, 0x38b8000
	s_addc_u32 vcc_hi, s7, 0
	s_nop 0
	v_lshl_add_u64 v[134:135], v[184:185], 0, vcc
	global_load_dwordx4 v[134:137], v[134:135], off offset:256
	v_mfma_f32_32x32x16_bf16 v[34:49], v[190:193], v[210:213], v[34:49]
	ds_write_b128 v189, v[146:149] offset:18432
	s_add_u32 vcc_lo, s6, 0x38c8000
	s_addc_u32 vcc_hi, s7, 0
	s_nop 0
	v_lshl_add_u64 v[138:139], v[184:185], 0, vcc
	global_load_dwordx4 v[138:141], v[138:139], off offset:256
	v_mfma_f32_32x32x16_bf16 v[2:17], v[194:197], v[210:213], v[2:17]
	s_waitcnt vmcnt(9)
	ds_write_b128 v189, v[150:153] offset:23040
	s_add_u32 vcc_lo, s6, 0x38d8000
	s_addc_u32 vcc_hi, s7, 0
	s_nop 0
	v_lshl_add_u64 v[142:143], v[184:185], 0, vcc
	global_load_dwordx4 v[142:145], v[142:143], off offset:256
	v_mfma_f32_32x32x16_bf16 v[114:129], v[214:217], v[224:227], v[114:129]
	s_waitcnt vmcnt(9)
	ds_write_b128 v189, v[154:157] offset:27648
	s_add_u32 vcc_lo, s6, 0x2828000
	s_addc_u32 vcc_hi, s7, 0
	s_nop 0
	v_lshl_add_u64 v[146:147], v[182:183], 0, vcc
	global_load_dwordx4 v[146:149], v[146:147], off offset:256
	v_mfma_f32_32x32x16_bf16 v[82:97], v[218:221], v[224:227], v[82:97]
	s_waitcnt vmcnt(9)
	ds_write_b128 v189, v[158:161] offset:32256
	s_add_u32 vcc_lo, s6, 0x2838000
	s_addc_u32 vcc_hi, s7, 0
	s_nop 0
	v_lshl_add_u64 v[150:151], v[182:183], 0, vcc
	global_load_dwordx4 v[150:153], v[150:151], off offset:256
	v_mfma_f32_32x32x16_bf16 v[98:113], v[214:217], v[234:237], v[98:113]
	s_waitcnt vmcnt(9)
	ds_write_b128 v189, v[162:165] offset:36864
	s_add_u32 vcc_lo, s6, 0x2848000
	s_addc_u32 vcc_hi, s7, 0
	s_nop 0
	v_lshl_add_u64 v[154:155], v[182:183], 0, vcc
	global_load_dwordx4 v[154:157], v[154:155], off offset:256
	v_mfma_f32_32x32x16_bf16 v[66:81], v[218:221], v[234:237], v[66:81]
	s_waitcnt vmcnt(9)
	ds_write_b128 v189, v[166:169] offset:41472
	s_add_u32 vcc_lo, s6, 0x2858000
	s_addc_u32 vcc_hi, s7, 0
	s_nop 0
	v_lshl_add_u64 v[158:159], v[182:183], 0, vcc
	global_load_dwordx4 v[158:161], v[158:159], off offset:256
	v_mfma_f32_32x32x16_bf16 v[50:65], v[214:217], v[238:241], v[50:65]
	s_waitcnt vmcnt(9)
	ds_write_b128 v189, v[170:173] offset:46080
	s_add_u32 vcc_lo, s6, 0x2868000
	s_addc_u32 vcc_hi, s7, 0
	s_nop 0
	v_lshl_add_u64 v[162:163], v[182:183], 0, vcc
	global_load_dwordx4 v[162:165], v[162:163], off offset:256
	v_mfma_f32_32x32x16_bf16 v[18:33], v[218:221], v[238:241], v[18:33]
	s_waitcnt vmcnt(9)
	ds_write_b128 v189, v[174:177] offset:50688
	s_add_u32 vcc_lo, s6, 0x2878000
	s_addc_u32 vcc_hi, s7, 0
	s_nop 0
	v_lshl_add_u64 v[166:167], v[182:183], 0, vcc
	global_load_dwordx4 v[166:169], v[166:167], off offset:256
	v_mfma_f32_32x32x16_bf16 v[34:49], v[214:217], v[242:245], v[34:49]
	s_add_u32 vcc_lo, s6, 0x2888000
	s_addc_u32 vcc_hi, s7, 0
	s_nop 0
	v_lshl_add_u64 v[170:171], v[182:183], 0, vcc
	global_load_dwordx4 v[170:173], v[170:171], off offset:256
	v_mfma_f32_32x32x16_bf16 v[2:17], v[218:221], v[242:245], v[2:17]
	s_add_u32 vcc_lo, s6, 0x2898000
	s_addc_u32 vcc_hi, s7, 0
	s_nop 0
	v_lshl_add_u64 v[174:175], v[182:183], 0, vcc
	global_load_dwordx4 v[174:177], v[174:175], off offset:256
	s_setprio 0
	s_branch .LBB0_65
; __device__ __forceinline__ void lds_barrier() { asm volatile("s_waitcnt lgkmcnt(0)\n\ts_barrier" ::: "memory"); }
; __device__ __forceinline__ f32x16 mfma32(bf16x8 a, bf16x8 b, f32x16 c) { return __builtin_amdgcn_mfma_f32_32x32x16_bf16(a, b, c, 0, 0, 0); }
; __device__ __forceinline__ void gemm_big(const bf16_t* __restrict__ A, long lda, const bf16_t* __restrict__ Bt, int K, f32x16 (&acc)[2][4], unsigned char* lds) {
;     ...
;             if (ks < 3) {
;                 af[nb][0] = *(const bf16x8*)(Ac + (ks + 1) * 16); af[nb][1] = *(const bf16x8*)(Ac + 32 * GLD + (ks + 1) * 16);
; #pragma unroll
;                 for (int ni = 0; ni < 4; ++ni) bfr[nb][ni] = *(const bf16x8*)(Bc + ni * 32 * GLD + (ks + 1) * 16);
;             }
;             __builtin_amdgcn_sched_barrier(0);
; #pragma unroll
;             for (int ni = 0; ni < 4; ++ni) { acc[0][ni] = mfma32(af[cb][0], bfr[cb][ni], acc[0][ni]); acc[1][ni] = mfma32(af[cb][1], bfr[cb][ni], acc[1][ni]); }
;             __builtin_amdgcn_sched_barrier(0);
;         }
;         __builtin_amdgcn_s_setprio(0);
;         lds_barrier();
;         if (kc + 1 < nk) {
;             lstore();
;             if (kc + 2 < nk) gload(kc + 2);
;             lds_barrier();
;         }
.Lmy_gB_7:
	v_mfma_f32_32x32x16_bf16 v[98:113], v[190:193], v[202:205], v[98:113]
	s_waitcnt vmcnt(9)
	ds_write_b128 v189, v[130:133]
	v_mfma_f32_32x32x16_bf16 v[66:81], v[194:197], v[202:205], v[66:81]
	ds_write_b128 v189, v[134:137] offset:4608
	v_mfma_f32_32x32x16_bf16 v[50:65], v[190:193], v[206:209], v[50:65]
	ds_write_b128 v189, v[138:141] offset:9216
	v_mfma_f32_32x32x16_bf16 v[18:33], v[194:197], v[206:209], v[18:33]
	s_waitcnt vmcnt(7)
	ds_write_b128 v189, v[142:145] offset:13824
	v_mfma_f32_32x32x16_bf16 v[34:49], v[190:193], v[210:213], v[34:49]
	ds_write_b128 v189, v[146:149] offset:18432
	v_mfma_f32_32x32x16_bf16 v[2:17], v[194:197], v[210:213], v[2:17]
	s_waitcnt vmcnt(6)
	ds_write_b128 v189, v[150:153] offset:23040
	v_mfma_f32_32x32x16_bf16 v[114:129], v[214:217], v[224:227], v[114:129]
	s_waitcnt vmcnt(5)
	ds_write_b128 v189, v[154:157] offset:27648
	v_mfma_f32_32x32x16_bf16 v[82:97], v[218:221], v[224:227], v[82:97]
	s_waitcnt vmcnt(4)
	ds_write_b128 v189, v[158:161] offset:32256
	v_mfma_f32_32x32x16_bf16 v[98:113], v[214:217], v[234:237], v[98:113]
	s_waitcnt vmcnt(3)
	ds_write_b128 v189, v[162:165] offset:36864
	v_mfma_f32_32x32x16_bf16 v[66:81], v[218:221], v[234:237], v[66:81]
	s_waitcnt vmcnt(2)
	ds_write_b128 v189, v[166:169] offset:41472
	v_mfma_f32_32x32x16_bf16 v[50:65], v[214:217], v[238:241], v[50:65]
	s_waitcnt vmcnt(1)
	ds_write_b128 v189, v[170:173] offset:46080
	v_mfma_f32_32x32x16_bf16 v[18:33], v[218:221], v[238:241], v[18:33]
	s_waitcnt vmcnt(0)
	ds_write_b128 v189, v[174:177] offset:50688
	v_mfma_f32_32x32x16_bf16 v[34:49], v[214:217], v[242:245], v[34:49]
	v_mfma_f32_32x32x16_bf16 v[2:17], v[218:221], v[242:245], v[2:17]
	s_setprio 0
	s_branch .LBB0_65

; __device__ __forceinline__ void lds_barrier() { asm volatile("s_waitcnt lgkmcnt(0)\n\ts_barrier" ::: "memory"); }
; __device__ __forceinline__ f32x16 mfma32(bf16x8 a, bf16x8 b, f32x16 c) { return __builtin_amdgcn_mfma_f32_32x32x16_bf16(a, b, c, 0, 0, 0); }
; __device__ __forceinline__ void gemm_big(const bf16_t* __restrict__ A, long lda, const bf16_t* __restrict__ Bt, int K, f32x16 (&acc)[2][4], unsigned char* lds) {
;     ...
;     for (int kc = 0; kc < nk; ++kc) {
;         bf16x8 af[2][2], bfr[2][4];
;         af[0][0] = *(const bf16x8*)(Ac); af[0][1] = *(const bf16x8*)(Ac + 32 * GLD);
; #pragma unroll
;         for (int ni = 0; ni < 4; ++ni) bfr[0][ni] = *(const bf16x8*)(Bc + ni * 32 * GLD);
;         __builtin_amdgcn_s_setprio(3);
; #pragma unroll
;         for (int ks = 0; ks < 4; ++ks) {
;             const int cb = ks & 1, nb = cb ^ 1;
;             if (ks < 3) {
;                 af[nb][0] = *(const bf16x8*)(Ac + (ks + 1) * 16); af[nb][1] = *(const bf16x8*)(Ac + 32 * GLD + (ks + 1) * 16);
; #pragma unroll
;                 for (int ni = 0; ni < 4; ++ni) bfr[nb][ni] = *(const bf16x8*)(Bc + ni * 32 * GLD + (ks + 1) * 16);
;             }
;             __builtin_amdgcn_sched_barrier(0);
; #pragma unroll
;             for (int ni = 0; ni < 4; ++ni) { acc[0][ni] = mfma32(af[cb][0], bfr[cb][ni], acc[0][ni]); acc[1][ni] = mfma32(af[cb][1], bfr[cb][ni], acc[1][ni]); }
;             __builtin_amdgcn_sched_barrier(0);
;         }
;         __builtin_amdgcn_s_setprio(0);
;         lds_barrier();
;         if (kc + 1 < nk) {
;             lstore();
;             if (kc + 2 < nk) gload(kc + 2);
;             lds_barrier();
;         }
.LBB0_84:
	s_cmp_gt_u32 s5, 14
	s_cbranch_scc1 .Lmy_gorig_6
	ds_read_b128 v[190:193], v187
	ds_read_b128 v[194:197], v187 offset:4608
	ds_read_b128 v[198:201], v188 offset:18432
	ds_read_b128 v[202:205], v188 offset:23040
	ds_read_b128 v[206:209], v188 offset:27648
	ds_read_b128 v[210:213], v188 offset:32256
	s_setprio 3
	ds_read_b128 v[214:217], v187 offset:32
	ds_read_b128 v[218:221], v187 offset:4640
	ds_read_b128 v[224:227], v188 offset:18464
	ds_read_b128 v[234:237], v188 offset:23072
	ds_read_b128 v[238:241], v188 offset:27680
	ds_read_b128 v[242:245], v188 offset:32288
	s_waitcnt lgkmcnt(9)
	v_mfma_f32_32x32x16_bf16 v[114:129], v[190:193], v[198:201], v[114:129]
	v_mfma_f32_32x32x16_bf16 v[50:65], v[194:197], v[198:201], v[50:65]
	s_waitcnt lgkmcnt(8)
	v_mfma_f32_32x32x16_bf16 v[98:113], v[190:193], v[202:205], v[98:113]
	v_mfma_f32_32x32x16_bf16 v[34:49], v[194:197], v[202:205], v[34:49]
	s_waitcnt lgkmcnt(7)
	v_mfma_f32_32x32x16_bf16 v[82:97], v[190:193], v[206:209], v[82:97]
	v_mfma_f32_32x32x16_bf16 v[18:33], v[194:197], v[206:209], v[18:33]
	s_waitcnt lgkmcnt(6)
	v_mfma_f32_32x32x16_bf16 v[66:81], v[190:193], v[210:213], v[66:81]
	v_mfma_f32_32x32x16_bf16 v[2:17], v[194:197], v[210:213], v[2:17]
	ds_read_b128 v[190:193], v187 offset:64
	ds_read_b128 v[194:197], v187 offset:4672
	ds_read_b128 v[198:201], v188 offset:18496
	ds_read_b128 v[202:205], v188 offset:23104
	ds_read_b128 v[206:209], v188 offset:27712
	ds_read_b128 v[210:213], v188 offset:32320
	s_waitcnt lgkmcnt(9)
	v_mfma_f32_32x32x16_bf16 v[114:129], v[214:217], v[224:227], v[114:129]
	v_mfma_f32_32x32x16_bf16 v[50:65], v[218:221], v[224:227], v[50:65]
	s_waitcnt lgkmcnt(8)
	v_mfma_f32_32x32x16_bf16 v[98:113], v[214:217], v[234:237], v[98:113]
	v_mfma_f32_32x32x16_bf16 v[34:49], v[218:221], v[234:237], v[34:49]
	s_waitcnt lgkmcnt(7)
	v_mfma_f32_32x32x16_bf16 v[82:97], v[214:217], v[238:241], v[82:97]
	v_mfma_f32_32x32x16_bf16 v[18:33], v[218:221], v[238:241], v[18:33]
	s_waitcnt lgkmcnt(6)
	v_mfma_f32_32x32x16_bf16 v[66:81], v[214:217], v[242:245], v[66:81]
	v_mfma_f32_32x32x16_bf16 v[2:17], v[218:221], v[242:245], v[2:17]
	ds_read_b128 v[214:217], v187 offset:96
	ds_read_b128 v[218:221], v187 offset:4704
	ds_read_b128 v[224:227], v188 offset:18528
	ds_read_b128 v[234:237], v188 offset:23136
	ds_read_b128 v[238:241], v188 offset:27744
	ds_read_b128 v[242:245], v188 offset:32352
	s_waitcnt lgkmcnt(9)
	v_mfma_f32_32x32x16_bf16 v[114:129], v[190:193], v[198:201], v[114:129]
	v_mfma_f32_32x32x16_bf16 v[50:65], v[194:197], v[198:201], v[50:65]
	s_waitcnt lgkmcnt(0)
	s_barrier
	s_cmpk_eq_i32 s6, 0x700
	s_cbranch_scc1 .Lmy_gB_6
	v_mfma_f32_32x32x16_bf16 v[98:113], v[190:193], v[202:205], v[98:113]
	s_waitcnt vmcnt(9)
	ds_write_b128 v189, v[130:133]
	v_mfma_f32_32x32x16_bf16 v[34:49], v[194:197], v[202:205], v[34:49]
	ds_write_b128 v189, v[134:137] offset:4608
	v_mfma_f32_32x32x16_bf16 v[82:97], v[190:193], v[206:209], v[82:97]
	ds_write_b128 v189, v[138:141] offset:9216
	s_add_u32 vcc_lo, s6, 0x14948000
	s_addc_u32 vcc_hi, s7, 0
	s_nop 0
	v_lshl_add_u64 v[130:131], v[184:185], 0, vcc
	global_load_dwordx4 v[130:133], v[130:131], off offset:256
	v_mfma_f32_32x32x16_bf16 v[18:33], v[194:197], v[206:209], v[18:33]
	s_waitcnt vmcnt(8)
	ds_write_b128 v189, v[142:145] offset:13824
	s_add_u32 vcc_lo, s6, 0x14958000
	s_addc_u32 vcc_hi, s7, 0
	s_nop 0
	v_lshl_add_u64 v[134:135], v[184:185], 0, vcc
	global_load_dwordx4 v[134:137], v[134:135], off offset:256
	v_mfma_f32_32x32x16_bf16 v[66:81], v[190:193], v[210:213], v[66:81]
	ds_write_b128 v189, v[146:149] offset:18432
	s_add_u32 vcc_lo, s6, 0x14968000
	s_addc_u32 vcc_hi, s7, 0
	s_nop 0
	v_lshl_add_u64 v[138:139], v[184:185], 0, vcc
	global_load_dwordx4 v[138:141], v[138:139], off offset:256
	v_mfma_f32_32x32x16_bf16 v[2:17], v[194:197], v[210:213], v[2:17]
	s_waitcnt vmcnt(9)
	ds_write_b128 v189, v[150:153] offset:23040
	s_add_u32 vcc_lo, s6, 0x14978000
	s_addc_u32 vcc_hi, s7, 0
	s_nop 0
	v_lshl_add_u64 v[142:143], v[184:185], 0, vcc
	global_load_dwordx4 v[142:145], v[142:143], off offset:256
	v_mfma_f32_32x32x16_bf16 v[114:129], v[214:217], v[224:227], v[114:129]
	s_waitcnt vmcnt(9)
	ds_write_b128 v189, v[154:157] offset:27648
	s_add_u32 vcc_lo, s6, 0x2628000
	s_addc_u32 vcc_hi, s7, 0
	s_nop 0
	v_lshl_add_u64 v[146:147], v[182:183], 0, vcc
	global_load_dwordx4 v[146:149], v[146:147], off offset:256
	v_mfma_f32_32x32x16_bf16 v[50:65], v[218:221], v[224:227], v[50:65]
	s_waitcnt vmcnt(9)
	ds_write_b128 v189, v[158:161] offset:32256
	s_add_u32 vcc_lo, s6, 0x2638000
	s_addc_u32 vcc_hi, s7, 0
	s_nop 0
	v_lshl_add_u64 v[150:151], v[182:183], 0, vcc
	global_load_dwordx4 v[150:153], v[150:151], off offset:256
	v_mfma_f32_32x32x16_bf16 v[98:113], v[214:217], v[234:237], v[98:113]
	s_waitcnt vmcnt(9)
	ds_write_b128 v189, v[162:165] offset:36864
	s_add_u32 vcc_lo, s6, 0x2648000
	s_addc_u32 vcc_hi, s7, 0
	s_nop 0
	v_lshl_add_u64 v[154:155], v[182:183], 0, vcc
	global_load_dwordx4 v[154:157], v[154:155], off offset:256
	v_mfma_f32_32x32x16_bf16 v[34:49], v[218:221], v[234:237], v[34:49]
	s_waitcnt vmcnt(9)
	ds_write_b128 v189, v[166:169] offset:41472
	s_add_u32 vcc_lo, s6, 0x2658000
	s_addc_u32 vcc_hi, s7, 0
	s_nop 0
	v_lshl_add_u64 v[158:159], v[182:183], 0, vcc
	global_load_dwordx4 v[158:161], v[158:159], off offset:256
	v_mfma_f32_32x32x16_bf16 v[82:97], v[214:217], v[238:241], v[82:97]
	s_waitcnt vmcnt(9)
	ds_write_b128 v189, v[170:173] offset:46080
	s_add_u32 vcc_lo, s6, 0x2668000
	s_addc_u32 vcc_hi, s7, 0
	s_nop 0
	v_lshl_add_u64 v[162:163], v[182:183], 0, vcc
	global_load_dwordx4 v[162:165], v[162:163], off offset:256
	v_mfma_f32_32x32x16_bf16 v[18:33], v[218:221], v[238:241], v[18:33]
	s_waitcnt vmcnt(9)
	ds_write_b128 v189, v[174:177] offset:50688
	s_add_u32 vcc_lo, s6, 0x2678000
	s_addc_u32 vcc_hi, s7, 0
	s_nop 0
	v_lshl_add_u64 v[166:167], v[182:183], 0, vcc
	global_load_dwordx4 v[166:169], v[166:167], off offset:256
	v_mfma_f32_32x32x16_bf16 v[66:81], v[214:217], v[242:245], v[66:81]
	s_add_u32 vcc_lo, s6, 0x2688000
	s_addc_u32 vcc_hi, s7, 0
	s_nop 0
	v_lshl_add_u64 v[170:171], v[182:183], 0, vcc
	global_load_dwordx4 v[170:173], v[170:171], off offset:256
	v_mfma_f32_32x32x16_bf16 v[2:17], v[218:221], v[242:245], v[2:17]
	s_add_u32 vcc_lo, s6, 0x2698000
	s_addc_u32 vcc_hi, s7, 0
	s_nop 0
	v_lshl_add_u64 v[174:175], v[182:183], 0, vcc
	global_load_dwordx4 v[174:177], v[174:175], off offset:256
	s_setprio 0
	s_branch .LBB0_82

; __device__ __forceinline__ void lds_barrier() { asm volatile("s_waitcnt lgkmcnt(0)\n\ts_barrier" ::: "memory"); }
; __device__ __forceinline__ f32x16 mfma32(bf16x8 a, bf16x8 b, f32x16 c) { return __builtin_amdgcn_mfma_f32_32x32x16_bf16(a, b, c, 0, 0, 0); }
; __device__ __forceinline__ void gemm_big(const bf16_t* __restrict__ A, long lda, const bf16_t* __restrict__ Bt, int K, f32x16 (&acc)[2][4], unsigned char* lds) {
;     ...
;     for (int kc = 0; kc < nk; ++kc) {
;         bf16x8 af[2][2], bfr[2][4];
;         af[0][0] = *(const bf16x8*)(Ac); af[0][1] = *(const bf16x8*)(Ac + 32 * GLD);
; #pragma unroll
;         for (int ni = 0; ni < 4; ++ni) bfr[0][ni] = *(const bf16x8*)(Bc + ni * 32 * GLD);
;         __builtin_amdgcn_s_setprio(3);
; #pragma unroll
;         for (int ks = 0; ks < 4; ++ks) {
;             const int cb = ks & 1, nb = cb ^ 1;
;             if (ks < 3) {
;                 af[nb][0] = *(const bf16x8*)(Ac + (ks + 1) * 16); af[nb][1] = *(const bf16x8*)(Ac + 32 * GLD + (ks + 1) * 16);
; #pragma unroll
;                 for (int ni = 0; ni < 4; ++ni) bfr[nb][ni] = *(const bf16x8*)(Bc + ni * 32 * GLD + (ks + 1) * 16);
;             }
;             __builtin_amdgcn_sched_barrier(0);
; #pragma unroll
;             for (int ni = 0; ni < 4; ++ni) { acc[0][ni] = mfma32(af[cb][0], bfr[cb][ni], acc[0][ni]); acc[1][ni] = mfma32(af[cb][1], bfr[cb][ni], acc[1][ni]); }
;             __builtin_amdgcn_sched_barrier(0);
;         }
;         __builtin_amdgcn_s_setprio(0);
;         lds_barrier();
;         if (kc + 1 < nk) {
;             lstore();
;             if (kc + 2 < nk) gload(kc + 2);
;             lds_barrier();
;         }
.LBB0_115:
	s_cmp_gt_u32 s5, 14
	s_cbranch_scc1 .Lmy_gorig_5
	ds_read_b128 v[190:193], v187
	ds_read_b128 v[194:197], v187 offset:4608
	ds_read_b128 v[198:201], v188 offset:18432
	ds_read_b128 v[202:205], v188 offset:23040
	ds_read_b128 v[206:209], v188 offset:27648
	ds_read_b128 v[210:213], v188 offset:32256
	s_setprio 3
	ds_read_b128 v[214:217], v187 offset:32
	ds_read_b128 v[218:221], v187 offset:4640
	ds_read_b128 v[224:227], v188 offset:18464
	ds_read_b128 v[234:237], v188 offset:23072
	ds_read_b128 v[238:241], v188 offset:27680
	ds_read_b128 v[242:245], v188 offset:32288
	s_waitcnt lgkmcnt(9)
	v_mfma_f32_32x32x16_bf16 v[114:129], v[190:193], v[198:201], v[114:129]
	v_mfma_f32_32x32x16_bf16 v[98:113], v[194:197], v[198:201], v[98:113]
	s_waitcnt lgkmcnt(8)
	v_mfma_f32_32x32x16_bf16 v[82:97], v[190:193], v[202:205], v[82:97]
	v_mfma_f32_32x32x16_bf16 v[66:81], v[194:197], v[202:205], v[66:81]
	s_waitcnt lgkmcnt(7)
	v_mfma_f32_32x32x16_bf16 v[50:65], v[190:193], v[206:209], v[50:65]
	v_mfma_f32_32x32x16_bf16 v[34:49], v[194:197], v[206:209], v[34:49]
	s_waitcnt lgkmcnt(6)
	v_mfma_f32_32x32x16_bf16 v[18:33], v[190:193], v[210:213], v[18:33]
	v_mfma_f32_32x32x16_bf16 v[2:17], v[194:197], v[210:213], v[2:17]
	ds_read_b128 v[190:193], v187 offset:64
	ds_read_b128 v[194:197], v187 offset:4672
	ds_read_b128 v[198:201], v188 offset:18496
	ds_read_b128 v[202:205], v188 offset:23104
	ds_read_b128 v[206:209], v188 offset:27712
	ds_read_b128 v[210:213], v188 offset:32320
	s_waitcnt lgkmcnt(9)
	v_mfma_f32_32x32x16_bf16 v[114:129], v[214:217], v[224:227], v[114:129]
	v_mfma_f32_32x32x16_bf16 v[98:113], v[218:221], v[224:227], v[98:113]
	s_waitcnt lgkmcnt(8)
	v_mfma_f32_32x32x16_bf16 v[82:97], v[214:217], v[234:237], v[82:97]
	v_mfma_f32_32x32x16_bf16 v[66:81], v[218:221], v[234:237], v[66:81]
	s_waitcnt lgkmcnt(7)
	v_mfma_f32_32x32x16_bf16 v[50:65], v[214:217], v[238:241], v[50:65]
	v_mfma_f32_32x32x16_bf16 v[34:49], v[218:221], v[238:241], v[34:49]
	s_waitcnt lgkmcnt(6)
	v_mfma_f32_32x32x16_bf16 v[18:33], v[214:217], v[242:245], v[18:33]
	v_mfma_f32_32x32x16_bf16 v[2:17], v[218:221], v[242:245], v[2:17]
	ds_read_b128 v[214:217], v187 offset:96
	ds_read_b128 v[218:221], v187 offset:4704
	ds_read_b128 v[224:227], v188 offset:18528
	ds_read_b128 v[234:237], v188 offset:23136
	ds_read_b128 v[238:241], v188 offset:27744
	ds_read_b128 v[242:245], v188 offset:32352
	s_waitcnt lgkmcnt(9)
	v_mfma_f32_32x32x16_bf16 v[114:129], v[190:193], v[198:201], v[114:129]
	v_mfma_f32_32x32x16_bf16 v[98:113], v[194:197], v[198:201], v[98:113]
	s_waitcnt lgkmcnt(0)
	s_barrier
	s_cmpk_eq_i32 s6, 0x700
	s_cbranch_scc1 .Lmy_gB_5
	v_mfma_f32_32x32x16_bf16 v[82:97], v[190:193], v[202:205], v[82:97]
	s_waitcnt vmcnt(9)
	ds_write_b128 v189, v[130:133]
	v_mfma_f32_32x32x16_bf16 v[66:81], v[194:197], v[202:205], v[66:81]
	ds_write_b128 v189, v[134:137] offset:4608
	v_mfma_f32_32x32x16_bf16 v[50:65], v[190:193], v[206:209], v[50:65]
	ds_write_b128 v189, v[138:141] offset:9216
	s_add_u32 vcc_lo, s6, 0x38a8000
	s_addc_u32 vcc_hi, s7, 0
	s_nop 0
	v_lshl_add_u64 v[130:131], v[184:185], 0, vcc
	global_load_dwordx4 v[130:133], v[130:131], off offset:256
	v_mfma_f32_32x32x16_bf16 v[34:49], v[194:197], v[206:209], v[34:49]
	s_waitcnt vmcnt(8)
	ds_write_b128 v189, v[142:145] offset:13824
	s_add_u32 vcc_lo, s6, 0x38b8000
	s_addc_u32 vcc_hi, s7, 0
	s_nop 0
	v_lshl_add_u64 v[134:135], v[184:185], 0, vcc
	global_load_dwordx4 v[134:137], v[134:135], off offset:256
	v_mfma_f32_32x32x16_bf16 v[18:33], v[190:193], v[210:213], v[18:33]
	ds_write_b128 v189, v[146:149] offset:18432
	s_add_u32 vcc_lo, s6, 0x38c8000
	s_addc_u32 vcc_hi, s7, 0
	s_nop 0
	v_lshl_add_u64 v[138:139], v[184:185], 0, vcc
	global_load_dwordx4 v[138:141], v[138:139], off offset:256
	v_mfma_f32_32x32x16_bf16 v[2:17], v[194:197], v[210:213], v[2:17]
	s_waitcnt vmcnt(9)
	ds_write_b128 v189, v[150:153] offset:23040
	s_add_u32 vcc_lo, s6, 0x38d8000
	s_addc_u32 vcc_hi, s7, 0
	s_nop 0
	v_lshl_add_u64 v[142:143], v[184:185], 0, vcc
	global_load_dwordx4 v[142:145], v[142:143], off offset:256
	v_mfma_f32_32x32x16_bf16 v[114:129], v[214:217], v[224:227], v[114:129]
	s_waitcnt vmcnt(9)
	ds_write_b128 v189, v[154:157] offset:27648
	s_add_u32 vcc_lo, s6, 0x1c88000
	s_addc_u32 vcc_hi, s7, 0
	s_nop 0
	v_lshl_add_u64 v[146:147], v[182:183], 0, vcc
	global_load_dwordx4 v[146:149], v[146:147], off offset:256
	v_mfma_f32_32x32x16_bf16 v[98:113], v[218:221], v[224:227], v[98:113]
	s_waitcnt vmcnt(9)
	ds_write_b128 v189, v[158:161] offset:32256
	s_add_u32 vcc_lo, s6, 0x1c98000
	s_addc_u32 vcc_hi, s7, 0
	s_nop 0
	v_lshl_add_u64 v[150:151], v[182:183], 0, vcc
	global_load_dwordx4 v[150:153], v[150:151], off offset:256
	v_mfma_f32_32x32x16_bf16 v[82:97], v[214:217], v[234:237], v[82:97]
	s_waitcnt vmcnt(9)
	ds_write_b128 v189, v[162:165] offset:36864
	s_add_u32 vcc_lo, s6, 0x1ca8000
	s_addc_u32 vcc_hi, s7, 0
	s_nop 0
	v_lshl_add_u64 v[154:155], v[182:183], 0, vcc
	global_load_dwordx4 v[154:157], v[154:155], off offset:256
	v_mfma_f32_32x32x16_bf16 v[66:81], v[218:221], v[234:237], v[66:81]
	s_waitcnt vmcnt(9)
	ds_write_b128 v189, v[166:169] offset:41472
	s_add_u32 vcc_lo, s6, 0x1cb8000
	s_addc_u32 vcc_hi, s7, 0
	s_nop 0
	v_lshl_add_u64 v[158:159], v[182:183], 0, vcc
	global_load_dwordx4 v[158:161], v[158:159], off offset:256
	v_mfma_f32_32x32x16_bf16 v[50:65], v[214:217], v[238:241], v[50:65]
	s_waitcnt vmcnt(9)
	ds_write_b128 v189, v[170:173] offset:46080
	s_add_u32 vcc_lo, s6, 0x1cc8000
	s_addc_u32 vcc_hi, s7, 0
	s_nop 0
	v_lshl_add_u64 v[162:163], v[182:183], 0, vcc
	global_load_dwordx4 v[162:165], v[162:163], off offset:256
	v_mfma_f32_32x32x16_bf16 v[34:49], v[218:221], v[238:241], v[34:49]
	s_waitcnt vmcnt(9)
	ds_write_b128 v189, v[174:177] offset:50688
	s_add_u32 vcc_lo, s6, 0x1cd8000
	s_addc_u32 vcc_hi, s7, 0
	s_nop 0
	v_lshl_add_u64 v[166:167], v[182:183], 0, vcc
	global_load_dwordx4 v[166:169], v[166:167], off offset:256
	v_mfma_f32_32x32x16_bf16 v[18:33], v[214:217], v[242:245], v[18:33]
	s_add_u32 vcc_lo, s6, 0x1ce8000
	s_addc_u32 vcc_hi, s7, 0
	s_nop 0
	v_lshl_add_u64 v[170:171], v[182:183], 0, vcc
	global_load_dwordx4 v[170:173], v[170:171], off offset:256
	v_mfma_f32_32x32x16_bf16 v[2:17], v[218:221], v[242:245], v[2:17]
	s_add_u32 vcc_lo, s6, 0x1cf8000
	s_addc_u32 vcc_hi, s7, 0
	s_nop 0
	v_lshl_add_u64 v[174:175], v[182:183], 0, vcc
	global_load_dwordx4 v[174:177], v[174:175], off offset:256
	s_setprio 0
	s_branch .LBB0_113
; __device__ __forceinline__ void lds_barrier() { asm volatile("s_waitcnt lgkmcnt(0)\n\ts_barrier" ::: "memory"); }
; __device__ __forceinline__ f32x16 mfma32(bf16x8 a, bf16x8 b, f32x16 c) { return __builtin_amdgcn_mfma_f32_32x32x16_bf16(a, b, c, 0, 0, 0); }
; __device__ __forceinline__ void gemm_big(const bf16_t* __restrict__ A, long lda, const bf16_t* __restrict__ Bt, int K, f32x16 (&acc)[2][4], unsigned char* lds) {
;     ...
;             if (ks < 3) {
;                 af[nb][0] = *(const bf16x8*)(Ac + (ks + 1) * 16); af[nb][1] = *(const bf16x8*)(Ac + 32 * GLD + (ks + 1) * 16);
; #pragma unroll
;                 for (int ni = 0; ni < 4; ++ni) bfr[nb][ni] = *(const bf16x8*)(Bc + ni * 32 * GLD + (ks + 1) * 16);
;             }
;             __builtin_amdgcn_sched_barrier(0);
; #pragma unroll
;             for (int ni = 0; ni < 4; ++ni) { acc[0][ni] = mfma32(af[cb][0], bfr[cb][ni], acc[0][ni]); acc[1][ni] = mfma32(af[cb][1], bfr[cb][ni], acc[1][ni]); }
;             __builtin_amdgcn_sched_barrier(0);
;         }
;         __builtin_amdgcn_s_setprio(0);
;         lds_barrier();
;         if (kc + 1 < nk) {
;             lstore();
;             if (kc + 2 < nk) gload(kc + 2);
;             lds_barrier();
;         }
.Lmy_gB_5:
	v_mfma_f32_32x32x16_bf16 v[82:97], v[190:193], v[202:205], v[82:97]
	s_waitcnt vmcnt(9)
	ds_write_b128 v189, v[130:133]
	v_mfma_f32_32x32x16_bf16 v[66:81], v[194:197], v[202:205], v[66:81]
	ds_write_b128 v189, v[134:137] offset:4608
	v_mfma_f32_32x32x16_bf16 v[50:65], v[190:193], v[206:209], v[50:65]
	ds_write_b128 v189, v[138:141] offset:9216
	v_mfma_f32_32x32x16_bf16 v[34:49], v[194:197], v[206:209], v[34:49]
	s_waitcnt vmcnt(7)
	ds_write_b128 v189, v[142:145] offset:13824
	v_mfma_f32_32x32x16_bf16 v[18:33], v[190:193], v[210:213], v[18:33]
	ds_write_b128 v189, v[146:149] offset:18432
	v_mfma_f32_32x32x16_bf16 v[2:17], v[194:197], v[210:213], v[2:17]
	s_waitcnt vmcnt(6)
	ds_write_b128 v189, v[150:153] offset:23040
	v_mfma_f32_32x32x16_bf16 v[114:129], v[214:217], v[224:227], v[114:129]
	s_waitcnt vmcnt(5)
	ds_write_b128 v189, v[154:157] offset:27648
	v_mfma_f32_32x32x16_bf16 v[98:113], v[218:221], v[224:227], v[98:113]
	s_waitcnt vmcnt(4)
	ds_write_b128 v189, v[158:161] offset:32256
	v_mfma_f32_32x32x16_bf16 v[82:97], v[214:217], v[234:237], v[82:97]
	s_waitcnt vmcnt(3)
	ds_write_b128 v189, v[162:165] offset:36864
	v_mfma_f32_32x32x16_bf16 v[66:81], v[218:221], v[234:237], v[66:81]
	s_waitcnt vmcnt(2)
	ds_write_b128 v189, v[166:169] offset:41472
	v_mfma_f32_32x32x16_bf16 v[50:65], v[214:217], v[238:241], v[50:65]
	s_waitcnt vmcnt(1)
	ds_write_b128 v189, v[170:173] offset:46080
	v_mfma_f32_32x32x16_bf16 v[34:49], v[218:221], v[238:241], v[34:49]
	s_waitcnt vmcnt(0)
	ds_write_b128 v189, v[174:177] offset:50688
	v_mfma_f32_32x32x16_bf16 v[18:33], v[214:217], v[242:245], v[18:33]
	v_mfma_f32_32x32x16_bf16 v[2:17], v[218:221], v[242:245], v[2:17]
	s_setprio 0
	s_branch .LBB0_113

; __device__ __forceinline__ void lds_barrier() { asm volatile("s_waitcnt lgkmcnt(0)\n\ts_barrier" ::: "memory"); }
; __device__ __forceinline__ f32x16 mfma32(bf16x8 a, bf16x8 b, f32x16 c) { return __builtin_amdgcn_mfma_f32_32x32x16_bf16(a, b, c, 0, 0, 0); }
; __device__ __forceinline__ void gemm_big(const bf16_t* __restrict__ A, long lda, const bf16_t* __restrict__ Bt, int K, f32x16 (&acc)[2][4], unsigned char* lds) {
;     ...
;     for (int kc = 0; kc < nk; ++kc) {
;         bf16x8 af[2][2], bfr[2][4];
;         af[0][0] = *(const bf16x8*)(Ac); af[0][1] = *(const bf16x8*)(Ac + 32 * GLD);
; #pragma unroll
;         for (int ni = 0; ni < 4; ++ni) bfr[0][ni] = *(const bf16x8*)(Bc + ni * 32 * GLD);
;         __builtin_amdgcn_s_setprio(3);
; #pragma unroll
;         for (int ks = 0; ks < 4; ++ks) {
;             const int cb = ks & 1, nb = cb ^ 1;
;             if (ks < 3) {
;                 af[nb][0] = *(const bf16x8*)(Ac + (ks + 1) * 16); af[nb][1] = *(const bf16x8*)(Ac + 32 * GLD + (ks + 1) * 16);
; #pragma unroll
;                 for (int ni = 0; ni < 4; ++ni) bfr[nb][ni] = *(const bf16x8*)(Bc + ni * 32 * GLD + (ks + 1) * 16);
;             }
;             __builtin_amdgcn_sched_barrier(0);
; #pragma unroll
;             for (int ni = 0; ni < 4; ++ni) { acc[0][ni] = mfma32(af[cb][0], bfr[cb][ni], acc[0][ni]); acc[1][ni] = mfma32(af[cb][1], bfr[cb][ni], acc[1][ni]); }
;             __builtin_amdgcn_sched_barrier(0);
;         }
;         __builtin_amdgcn_s_setprio(0);
;         lds_barrier();
;         if (kc + 1 < nk) {
;             lstore();
;             if (kc + 2 < nk) gload(kc + 2);
;             lds_barrier();
;         }
.LBB0_283:
	s_cmp_gt_u32 s5, 2
	s_cbranch_scc1 .Lmy_gorig_3
	ds_read_b128 v[192:195], v189
	ds_read_b128 v[196:199], v189 offset:4608
	ds_read_b128 v[200:203], v190 offset:18432
	ds_read_b128 v[204:207], v190 offset:23040
	ds_read_b128 v[208:211], v190 offset:27648
	ds_read_b128 v[212:215], v190 offset:32256
	s_setprio 3
	ds_read_b128 v[216:219], v189 offset:32
	ds_read_b128 v[224:227], v189 offset:4640
	ds_read_b128 v[234:237], v190 offset:18464
	ds_read_b128 v[238:241], v190 offset:23072
	ds_read_b128 v[242:245], v190 offset:27680
	ds_read_b128 v[246:249], v190 offset:32288
	s_waitcnt lgkmcnt(9)
	v_mfma_f32_32x32x16_bf16 v[114:129], v[192:195], v[200:203], v[114:129]
	v_mfma_f32_32x32x16_bf16 v[50:65], v[196:199], v[200:203], v[50:65]
	s_waitcnt lgkmcnt(8)
	v_mfma_f32_32x32x16_bf16 v[98:113], v[192:195], v[204:207], v[98:113]
	v_mfma_f32_32x32x16_bf16 v[34:49], v[196:199], v[204:207], v[34:49]
	s_waitcnt lgkmcnt(7)
	v_mfma_f32_32x32x16_bf16 v[82:97], v[192:195], v[208:211], v[82:97]
	v_mfma_f32_32x32x16_bf16 v[18:33], v[196:199], v[208:211], v[18:33]
	s_waitcnt lgkmcnt(6)
	v_mfma_f32_32x32x16_bf16 v[66:81], v[192:195], v[212:215], v[66:81]
	v_mfma_f32_32x32x16_bf16 v[2:17], v[196:199], v[212:215], v[2:17]
	ds_read_b128 v[192:195], v189 offset:64
	ds_read_b128 v[196:199], v189 offset:4672
	ds_read_b128 v[200:203], v190 offset:18496
	ds_read_b128 v[204:207], v190 offset:23104
	ds_read_b128 v[208:211], v190 offset:27712
	ds_read_b128 v[212:215], v190 offset:32320
	s_waitcnt lgkmcnt(9)
	v_mfma_f32_32x32x16_bf16 v[114:129], v[216:219], v[234:237], v[114:129]
	v_mfma_f32_32x32x16_bf16 v[50:65], v[224:227], v[234:237], v[50:65]
	s_waitcnt lgkmcnt(8)
	v_mfma_f32_32x32x16_bf16 v[98:113], v[216:219], v[238:241], v[98:113]
	v_mfma_f32_32x32x16_bf16 v[34:49], v[224:227], v[238:241], v[34:49]
	s_waitcnt lgkmcnt(7)
	v_mfma_f32_32x32x16_bf16 v[82:97], v[216:219], v[242:245], v[82:97]
	v_mfma_f32_32x32x16_bf16 v[18:33], v[224:227], v[242:245], v[18:33]
	s_waitcnt lgkmcnt(6)
	v_mfma_f32_32x32x16_bf16 v[66:81], v[216:219], v[246:249], v[66:81]
	v_mfma_f32_32x32x16_bf16 v[2:17], v[224:227], v[246:249], v[2:17]
	ds_read_b128 v[216:219], v189 offset:96
	ds_read_b128 v[224:227], v189 offset:4704
	ds_read_b128 v[234:237], v190 offset:18528
	ds_read_b128 v[238:241], v190 offset:23136
	ds_read_b128 v[242:245], v190 offset:27744
	ds_read_b128 v[246:249], v190 offset:32352
	s_waitcnt lgkmcnt(9)
	v_mfma_f32_32x32x16_bf16 v[114:129], v[192:195], v[200:203], v[114:129]
	v_mfma_f32_32x32x16_bf16 v[50:65], v[196:199], v[200:203], v[50:65]
	s_waitcnt lgkmcnt(0)
	s_barrier
	s_cmpk_eq_i32 s6, 0x100
	s_cbranch_scc1 .Lmy_gB_3
	v_mfma_f32_32x32x16_bf16 v[98:113], v[192:195], v[204:207], v[98:113]
	s_waitcnt vmcnt(9)
	ds_write_b128 v191, v[130:133]
	v_mfma_f32_32x32x16_bf16 v[34:49], v[196:199], v[204:207], v[34:49]
	ds_write_b128 v191, v[134:137] offset:4608
	v_mfma_f32_32x32x16_bf16 v[82:97], v[192:195], v[208:211], v[82:97]
	ds_write_b128 v191, v[138:141] offset:9216
	s_add_u32 vcc_lo, s6, 0x78a8000
	s_addc_u32 vcc_hi, s7, 0
	s_nop 0
	v_lshl_add_u64 v[130:131], v[184:185], 0, vcc
	global_load_dwordx4 v[130:133], v[130:131], off offset:3328
	v_mfma_f32_32x32x16_bf16 v[18:33], v[196:199], v[208:211], v[18:33]
	s_waitcnt vmcnt(8)
	ds_write_b128 v191, v[142:145] offset:13824
	s_add_u32 vcc_lo, s6, 0x78e6000
	s_addc_u32 vcc_hi, s7, 0
	s_nop 0
	v_lshl_add_u64 v[134:135], v[184:185], 0, vcc
	global_load_dwordx4 v[134:137], v[134:135], off offset:3328
	v_mfma_f32_32x32x16_bf16 v[66:81], v[192:195], v[212:215], v[66:81]
	ds_write_b128 v191, v[146:149] offset:18432
	s_add_u32 vcc_lo, s6, 0x7924000
	s_addc_u32 vcc_hi, s7, 0
	s_nop 0
	v_lshl_add_u64 v[138:139], v[184:185], 0, vcc
	global_load_dwordx4 v[138:141], v[138:139], off offset:3328
	v_mfma_f32_32x32x16_bf16 v[2:17], v[196:199], v[212:215], v[2:17]
	s_waitcnt vmcnt(9)
	ds_write_b128 v191, v[150:153] offset:23040
	s_add_u32 vcc_lo, s6, 0x7962000
	s_addc_u32 vcc_hi, s7, 0
	s_nop 0
	v_lshl_add_u64 v[142:143], v[184:185], 0, vcc
	global_load_dwordx4 v[142:145], v[142:143], off offset:3328
	v_mfma_f32_32x32x16_bf16 v[114:129], v[216:219], v[234:237], v[114:129]
	s_waitcnt vmcnt(9)
	ds_write_b128 v191, v[154:157] offset:27648
	s_add_u32 vcc_lo, s6, 0x2288000
	s_addc_u32 vcc_hi, s7, 0
	s_nop 0
	v_lshl_add_u64 v[146:147], v[182:183], 0, vcc
	global_load_dwordx4 v[146:149], v[146:147], off offset:256
	v_mfma_f32_32x32x16_bf16 v[50:65], v[224:227], v[234:237], v[50:65]
	s_waitcnt vmcnt(9)
	ds_write_b128 v191, v[158:161] offset:32256
	s_add_u32 vcc_lo, s6, 0x228c000
	s_addc_u32 vcc_hi, s7, 0
	s_nop 0
	v_lshl_add_u64 v[150:151], v[182:183], 0, vcc
	global_load_dwordx4 v[150:153], v[150:151], off offset:256
	v_mfma_f32_32x32x16_bf16 v[98:113], v[216:219], v[238:241], v[98:113]
	s_waitcnt vmcnt(9)
	ds_write_b128 v191, v[162:165] offset:36864
	s_add_u32 vcc_lo, s6, 0x2290000
	s_addc_u32 vcc_hi, s7, 0
	s_nop 0
	v_lshl_add_u64 v[154:155], v[182:183], 0, vcc
	global_load_dwordx4 v[154:157], v[154:155], off offset:256
	v_mfma_f32_32x32x16_bf16 v[34:49], v[224:227], v[238:241], v[34:49]
	s_waitcnt vmcnt(9)
	ds_write_b128 v191, v[166:169] offset:41472
	s_add_u32 vcc_lo, s6, 0x2294000
	s_addc_u32 vcc_hi, s7, 0
	s_nop 0
	v_lshl_add_u64 v[158:159], v[182:183], 0, vcc
	global_load_dwordx4 v[158:161], v[158:159], off offset:256
	v_mfma_f32_32x32x16_bf16 v[82:97], v[216:219], v[242:245], v[82:97]
	s_waitcnt vmcnt(9)
	ds_write_b128 v191, v[170:173] offset:46080
	s_add_u32 vcc_lo, s6, 0x2298000
	s_addc_u32 vcc_hi, s7, 0
	s_nop 0
	v_lshl_add_u64 v[162:163], v[182:183], 0, vcc
	global_load_dwordx4 v[162:165], v[162:163], off offset:256
	v_mfma_f32_32x32x16_bf16 v[18:33], v[224:227], v[242:245], v[18:33]
	s_waitcnt vmcnt(9)
	ds_write_b128 v191, v[174:177] offset:50688
	s_add_u32 vcc_lo, s6, 0x229c000
	s_addc_u32 vcc_hi, s7, 0
	s_nop 0
	v_lshl_add_u64 v[166:167], v[182:183], 0, vcc
	global_load_dwordx4 v[166:169], v[166:167], off offset:256
	v_mfma_f32_32x32x16_bf16 v[66:81], v[216:219], v[246:249], v[66:81]
	s_add_u32 vcc_lo, s6, 0x22a0000
	s_addc_u32 vcc_hi, s7, 0
	s_nop 0
	v_lshl_add_u64 v[170:171], v[182:183], 0, vcc
	global_load_dwordx4 v[170:173], v[170:171], off offset:256
	v_mfma_f32_32x32x16_bf16 v[2:17], v[224:227], v[246:249], v[2:17]
	s_add_u32 vcc_lo, s6, 0x22a4000
	s_addc_u32 vcc_hi, s7, 0
	s_nop 0
	v_lshl_add_u64 v[174:175], v[182:183], 0, vcc
	global_load_dwordx4 v[174:177], v[174:175], off offset:256
	s_setprio 0
	s_branch .LBB0_281
; __device__ __forceinline__ void lds_barrier() { asm volatile("s_waitcnt lgkmcnt(0)\n\ts_barrier" ::: "memory"); }
; __device__ __forceinline__ f32x16 mfma32(bf16x8 a, bf16x8 b, f32x16 c) { return __builtin_amdgcn_mfma_f32_32x32x16_bf16(a, b, c, 0, 0, 0); }
; __device__ __forceinline__ void gemm_big(const bf16_t* __restrict__ A, long lda, const bf16_t* __restrict__ Bt, int K, f32x16 (&acc)[2][4], unsigned char* lds) {
;     ...
;         for (int ks = 0; ks < 4; ++ks) {
;             const int cb = ks & 1, nb = cb ^ 1;
;             if (ks < 3) {
;                 af[nb][0] = *(const bf16x8*)(Ac + (ks + 1) * 16); af[nb][1] = *(const bf16x8*)(Ac + 32 * GLD + (ks + 1) * 16);
; #pragma unroll
;                 for (int ni = 0; ni < 4; ++ni) bfr[nb][ni] = *(const bf16x8*)(Bc + ni * 32 * GLD + (ks + 1) * 16);
;             }
;             __builtin_amdgcn_sched_barrier(0);
; #pragma unroll
;             for (int ni = 0; ni < 4; ++ni) { acc[0][ni] = mfma32(af[cb][0], bfr[cb][ni], acc[0][ni]); acc[1][ni] = mfma32(af[cb][1], bfr[cb][ni], acc[1][ni]); }
;             __builtin_amdgcn_sched_barrier(0);
;         }
;         __builtin_amdgcn_s_setprio(0);
;         lds_barrier();
;         if (kc + 1 < nk) {
;             lstore();
;             if (kc + 2 < nk) gload(kc + 2);
;             lds_barrier();
;         }
.Lmy_gB_3:
	v_mfma_f32_32x32x16_bf16 v[98:113], v[192:195], v[204:207], v[98:113]
	s_waitcnt vmcnt(9)
	ds_write_b128 v191, v[130:133]
	v_mfma_f32_32x32x16_bf16 v[34:49], v[196:199], v[204:207], v[34:49]
	ds_write_b128 v191, v[134:137] offset:4608
	v_mfma_f32_32x32x16_bf16 v[82:97], v[192:195], v[208:211], v[82:97]
	ds_write_b128 v191, v[138:141] offset:9216
	v_mfma_f32_32x32x16_bf16 v[18:33], v[196:199], v[208:211], v[18:33]
	s_waitcnt vmcnt(7)
	ds_write_b128 v191, v[142:145] offset:13824
	v_mfma_f32_32x32x16_bf16 v[66:81], v[192:195], v[212:215], v[66:81]
	ds_write_b128 v191, v[146:149] offset:18432
	v_mfma_f32_32x32x16_bf16 v[2:17], v[196:199], v[212:215], v[2:17]
	s_waitcnt vmcnt(6)
	ds_write_b128 v191, v[150:153] offset:23040
	v_mfma_f32_32x32x16_bf16 v[114:129], v[216:219], v[234:237], v[114:129]
	s_waitcnt vmcnt(5)
	ds_write_b128 v191, v[154:157] offset:27648
	v_mfma_f32_32x32x16_bf16 v[50:65], v[224:227], v[234:237], v[50:65]
	s_waitcnt vmcnt(4)
	ds_write_b128 v191, v[158:161] offset:32256
	v_mfma_f32_32x32x16_bf16 v[98:113], v[216:219], v[238:241], v[98:113]
	s_waitcnt vmcnt(3)
	ds_write_b128 v191, v[162:165] offset:36864
	v_mfma_f32_32x32x16_bf16 v[34:49], v[224:227], v[238:241], v[34:49]
	s_waitcnt vmcnt(2)
	ds_write_b128 v191, v[166:169] offset:41472
	v_mfma_f32_32x32x16_bf16 v[82:97], v[216:219], v[242:245], v[82:97]
	s_waitcnt vmcnt(1)
	ds_write_b128 v191, v[170:173] offset:46080
	v_mfma_f32_32x32x16_bf16 v[18:33], v[224:227], v[242:245], v[18:33]
	s_waitcnt vmcnt(0)
	ds_write_b128 v191, v[174:177] offset:50688
	v_mfma_f32_32x32x16_bf16 v[66:81], v[216:219], v[246:249], v[66:81]
	v_mfma_f32_32x32x16_bf16 v[2:17], v[224:227], v[246:249], v[2:17]
	s_setprio 0
	s_branch .LBB0_281

; __device__ __forceinline__ void lds_barrier() { asm volatile("s_waitcnt lgkmcnt(0)\n\ts_barrier" ::: "memory"); }
; __device__ __forceinline__ f32x16 mfma32(bf16x8 a, bf16x8 b, f32x16 c) { return __builtin_amdgcn_mfma_f32_32x32x16_bf16(a, b, c, 0, 0, 0); }
; __device__ __forceinline__ void gemm_big(const bf16_t* __restrict__ A, long lda, const bf16_t* __restrict__ Bt, int K, f32x16 (&acc)[2][4], unsigned char* lds) {
;     ...
;     for (int kc = 0; kc < nk; ++kc) {
;         bf16x8 af[2][2], bfr[2][4];
;         af[0][0] = *(const bf16x8*)(Ac); af[0][1] = *(const bf16x8*)(Ac + 32 * GLD);
; #pragma unroll
;         for (int ni = 0; ni < 4; ++ni) bfr[0][ni] = *(const bf16x8*)(Bc + ni * 32 * GLD);
;         __builtin_amdgcn_s_setprio(3);
; #pragma unroll
;         for (int ks = 0; ks < 4; ++ks) {
;             const int cb = ks & 1, nb = cb ^ 1;
;             if (ks < 3) {
;                 af[nb][0] = *(const bf16x8*)(Ac + (ks + 1) * 16); af[nb][1] = *(const bf16x8*)(Ac + 32 * GLD + (ks + 1) * 16);
; #pragma unroll
;                 for (int ni = 0; ni < 4; ++ni) bfr[nb][ni] = *(const bf16x8*)(Bc + ni * 32 * GLD + (ks + 1) * 16);
;             }
;             __builtin_amdgcn_sched_barrier(0);
; #pragma unroll
;             for (int ni = 0; ni < 4; ++ni) { acc[0][ni] = mfma32(af[cb][0], bfr[cb][ni], acc[0][ni]); acc[1][ni] = mfma32(af[cb][1], bfr[cb][ni], acc[1][ni]); }
;             __builtin_amdgcn_sched_barrier(0);
;         }
;         __builtin_amdgcn_s_setprio(0);
;         lds_barrier();
;         if (kc + 1 < nk) {
;             lstore();
;             if (kc + 2 < nk) gload(kc + 2);
;             lds_barrier();
;         }
;     }
.LBB0_678:
	s_cmp_gt_u32 s6, 14
	s_cbranch_scc1 .Lmy_gorig_2
	ds_read_b128 v[192:195], v189
	ds_read_b128 v[196:199], v189 offset:4608
	ds_read_b128 v[200:203], v190 offset:18432
	ds_read_b128 v[204:207], v190 offset:23040
	ds_read_b128 v[208:211], v190 offset:27648
	ds_read_b128 v[212:215], v190 offset:32256
	s_setprio 3
	ds_read_b128 v[216:219], v189 offset:32
	ds_read_b128 v[234:237], v189 offset:4640
	ds_read_b128 v[238:241], v190 offset:18464
	ds_read_b128 v[242:245], v190 offset:23072
	ds_read_b128 v[246:249], v190 offset:27680
	ds_read_b128 v[224:227], v190 offset:32288
	s_waitcnt lgkmcnt(9)
	v_mfma_f32_32x32x16_bf16 v[114:129], v[192:195], v[200:203], v[114:129]
	v_mfma_f32_32x32x16_bf16 v[98:113], v[196:199], v[200:203], v[98:113]
	s_waitcnt lgkmcnt(8)
	v_mfma_f32_32x32x16_bf16 v[82:97], v[192:195], v[204:207], v[82:97]
	v_mfma_f32_32x32x16_bf16 v[66:81], v[196:199], v[204:207], v[66:81]
	s_waitcnt lgkmcnt(7)
	v_mfma_f32_32x32x16_bf16 v[50:65], v[192:195], v[208:211], v[50:65]
	v_mfma_f32_32x32x16_bf16 v[34:49], v[196:199], v[208:211], v[34:49]
	s_waitcnt lgkmcnt(6)
	v_mfma_f32_32x32x16_bf16 v[18:33], v[192:195], v[212:215], v[18:33]
	v_mfma_f32_32x32x16_bf16 v[2:17], v[196:199], v[212:215], v[2:17]
	ds_read_b128 v[192:195], v189 offset:64
	ds_read_b128 v[196:199], v189 offset:4672
	ds_read_b128 v[200:203], v190 offset:18496
	ds_read_b128 v[204:207], v190 offset:23104
	ds_read_b128 v[208:211], v190 offset:27712
	ds_read_b128 v[212:215], v190 offset:32320
	s_waitcnt lgkmcnt(9)
	v_mfma_f32_32x32x16_bf16 v[114:129], v[216:219], v[238:241], v[114:129]
	v_mfma_f32_32x32x16_bf16 v[98:113], v[234:237], v[238:241], v[98:113]
	s_waitcnt lgkmcnt(8)
	v_mfma_f32_32x32x16_bf16 v[82:97], v[216:219], v[242:245], v[82:97]
	v_mfma_f32_32x32x16_bf16 v[66:81], v[234:237], v[242:245], v[66:81]
	s_waitcnt lgkmcnt(7)
	v_mfma_f32_32x32x16_bf16 v[50:65], v[216:219], v[246:249], v[50:65]
	v_mfma_f32_32x32x16_bf16 v[34:49], v[234:237], v[246:249], v[34:49]
	s_waitcnt lgkmcnt(6)
	v_mfma_f32_32x32x16_bf16 v[18:33], v[216:219], v[224:227], v[18:33]
	v_mfma_f32_32x32x16_bf16 v[2:17], v[234:237], v[224:227], v[2:17]
	ds_read_b128 v[216:219], v189 offset:96
	ds_read_b128 v[224:227], v189 offset:4704
	ds_read_b128 v[234:237], v190 offset:18528
	ds_read_b128 v[238:241], v190 offset:23136
	ds_read_b128 v[242:245], v190 offset:27744
	ds_read_b128 v[246:249], v190 offset:32352
	s_waitcnt lgkmcnt(9)
	v_mfma_f32_32x32x16_bf16 v[114:129], v[192:195], v[200:203], v[114:129]
	v_mfma_f32_32x32x16_bf16 v[98:113], v[196:199], v[200:203], v[98:113]
	s_waitcnt lgkmcnt(0)
	s_barrier
	s_cmpk_eq_i32 s0, 0x700
	s_cbranch_scc1 .Lmy_gB_2
	v_mfma_f32_32x32x16_bf16 v[82:97], v[192:195], v[204:207], v[82:97]
	s_waitcnt vmcnt(9)
	ds_write_b128 v188, v[130:133]
	v_mfma_f32_32x32x16_bf16 v[66:81], v[196:199], v[204:207], v[66:81]
	ds_write_b128 v188, v[134:137] offset:4608
	v_mfma_f32_32x32x16_bf16 v[50:65], v[192:195], v[208:211], v[50:65]
	ds_write_b128 v188, v[138:141] offset:9216
	s_add_u32 vcc_lo, s0, 0x38a8000
	s_addc_u32 vcc_hi, s1, 0
	s_nop 0
	v_lshl_add_u64 v[130:131], v[184:185], 0, vcc
	global_load_dwordx4 v[130:133], v[130:131], off offset:256
	v_mfma_f32_32x32x16_bf16 v[34:49], v[196:199], v[208:211], v[34:49]
	s_waitcnt vmcnt(8)
	ds_write_b128 v188, v[142:145] offset:13824
	s_add_u32 vcc_lo, s0, 0x38b8000
	s_addc_u32 vcc_hi, s1, 0
	s_nop 0
	v_lshl_add_u64 v[134:135], v[184:185], 0, vcc
	global_load_dwordx4 v[134:137], v[134:135], off offset:256
	v_mfma_f32_32x32x16_bf16 v[18:33], v[192:195], v[212:215], v[18:33]
	ds_write_b128 v188, v[146:149] offset:18432
	s_add_u32 vcc_lo, s0, 0x38c8000
	s_addc_u32 vcc_hi, s1, 0
	s_nop 0
	v_lshl_add_u64 v[138:139], v[184:185], 0, vcc
	global_load_dwordx4 v[138:141], v[138:139], off offset:256
	v_mfma_f32_32x32x16_bf16 v[2:17], v[196:199], v[212:215], v[2:17]
	s_waitcnt vmcnt(9)
	ds_write_b128 v188, v[150:153] offset:23040
	s_add_u32 vcc_lo, s0, 0x38d8000
	s_addc_u32 vcc_hi, s1, 0
	s_nop 0
	v_lshl_add_u64 v[142:143], v[184:185], 0, vcc
	global_load_dwordx4 v[142:145], v[142:143], off offset:256
	v_mfma_f32_32x32x16_bf16 v[114:129], v[216:219], v[234:237], v[114:129]
	s_waitcnt vmcnt(9)
	ds_write_b128 v188, v[154:157] offset:27648
	s_add_u32 vcc_lo, s0, 0x1488000
	s_addc_u32 vcc_hi, s1, 0
	s_nop 0
	v_lshl_add_u64 v[146:147], v[182:183], 0, vcc
	global_load_dwordx4 v[146:149], v[146:147], off offset:256
	v_mfma_f32_32x32x16_bf16 v[98:113], v[224:227], v[234:237], v[98:113]
	s_waitcnt vmcnt(9)
	ds_write_b128 v188, v[158:161] offset:32256
	s_add_u32 vcc_lo, s0, 0x1498000
	s_addc_u32 vcc_hi, s1, 0
	s_nop 0
	v_lshl_add_u64 v[150:151], v[182:183], 0, vcc
	global_load_dwordx4 v[150:153], v[150:151], off offset:256
	v_mfma_f32_32x32x16_bf16 v[82:97], v[216:219], v[238:241], v[82:97]
	s_waitcnt vmcnt(9)
	ds_write_b128 v188, v[162:165] offset:36864
	s_add_u32 vcc_lo, s0, 0x14a8000
	s_addc_u32 vcc_hi, s1, 0
	s_nop 0
	v_lshl_add_u64 v[154:155], v[182:183], 0, vcc
	global_load_dwordx4 v[154:157], v[154:155], off offset:256
	v_mfma_f32_32x32x16_bf16 v[66:81], v[224:227], v[238:241], v[66:81]
	s_waitcnt vmcnt(9)
	ds_write_b128 v188, v[166:169] offset:41472
	s_add_u32 vcc_lo, s0, 0x14b8000
	s_addc_u32 vcc_hi, s1, 0
	s_nop 0
	v_lshl_add_u64 v[158:159], v[182:183], 0, vcc
	global_load_dwordx4 v[158:161], v[158:159], off offset:256
	v_mfma_f32_32x32x16_bf16 v[50:65], v[216:219], v[242:245], v[50:65]
	s_waitcnt vmcnt(9)
	ds_write_b128 v188, v[170:173] offset:46080
	s_add_u32 vcc_lo, s0, 0x14c8000
	s_addc_u32 vcc_hi, s1, 0
	s_nop 0
	v_lshl_add_u64 v[162:163], v[182:183], 0, vcc
	global_load_dwordx4 v[162:165], v[162:163], off offset:256
	v_mfma_f32_32x32x16_bf16 v[34:49], v[224:227], v[242:245], v[34:49]
	s_waitcnt vmcnt(9)
	ds_write_b128 v188, v[174:177] offset:50688
	s_add_u32 vcc_lo, s0, 0x14d8000
	s_addc_u32 vcc_hi, s1, 0
	s_nop 0
	v_lshl_add_u64 v[166:167], v[182:183], 0, vcc
	global_load_dwordx4 v[166:169], v[166:167], off offset:256
	v_mfma_f32_32x32x16_bf16 v[18:33], v[216:219], v[246:249], v[18:33]
	s_add_u32 vcc_lo, s0, 0x14e8000
	s_addc_u32 vcc_hi, s1, 0
	s_nop 0
	v_lshl_add_u64 v[170:171], v[182:183], 0, vcc
	global_load_dwordx4 v[170:173], v[170:171], off offset:256
	v_mfma_f32_32x32x16_bf16 v[2:17], v[224:227], v[246:249], v[2:17]
	s_add_u32 vcc_lo, s0, 0x14f8000
	s_addc_u32 vcc_hi, s1, 0
	s_nop 0
	v_lshl_add_u64 v[174:175], v[182:183], 0, vcc
	global_load_dwordx4 v[174:177], v[174:175], off offset:256
	s_setprio 0
	s_branch .LBB0_676
; __device__ __forceinline__ void lds_barrier() { asm volatile("s_waitcnt lgkmcnt(0)\n\ts_barrier" ::: "memory"); }
; __device__ __forceinline__ f32x16 mfma32(bf16x8 a, bf16x8 b, f32x16 c) { return __builtin_amdgcn_mfma_f32_32x32x16_bf16(a, b, c, 0, 0, 0); }
; __device__ __forceinline__ void gemm_big(const bf16_t* __restrict__ A, long lda, const bf16_t* __restrict__ Bt, int K, f32x16 (&acc)[2][4], unsigned char* lds) {
;     ...
;         for (int ks = 0; ks < 4; ++ks) {
;             const int cb = ks & 1, nb = cb ^ 1;
;             if (ks < 3) {
;                 af[nb][0] = *(const bf16x8*)(Ac + (ks + 1) * 16); af[nb][1] = *(const bf16x8*)(Ac + 32 * GLD + (ks + 1) * 16);
; #pragma unroll
;                 for (int ni = 0; ni < 4; ++ni) bfr[nb][ni] = *(const bf16x8*)(Bc + ni * 32 * GLD + (ks + 1) * 16);
;             }
;             __builtin_amdgcn_sched_barrier(0);
; #pragma unroll
;             for (int ni = 0; ni < 4; ++ni) { acc[0][ni] = mfma32(af[cb][0], bfr[cb][ni], acc[0][ni]); acc[1][ni] = mfma32(af[cb][1], bfr[cb][ni], acc[1][ni]); }
;             __builtin_amdgcn_sched_barrier(0);
;         }
;         __builtin_amdgcn_s_setprio(0);
;         lds_barrier();
;         if (kc + 1 < nk) {
;             lstore();
;             if (kc + 2 < nk) gload(kc + 2);
;             lds_barrier();
;         }
.Lmy_gB_2:
	v_mfma_f32_32x32x16_bf16 v[82:97], v[192:195], v[204:207], v[82:97]
	s_waitcnt vmcnt(9)
	ds_write_b128 v188, v[130:133]
	v_mfma_f32_32x32x16_bf16 v[66:81], v[196:199], v[204:207], v[66:81]
	ds_write_b128 v188, v[134:137] offset:4608
	v_mfma_f32_32x32x16_bf16 v[50:65], v[192:195], v[208:211], v[50:65]
	ds_write_b128 v188, v[138:141] offset:9216
	v_mfma_f32_32x32x16_bf16 v[34:49], v[196:199], v[208:211], v[34:49]
	s_waitcnt vmcnt(7)
	ds_write_b128 v188, v[142:145] offset:13824
	v_mfma_f32_32x32x16_bf16 v[18:33], v[192:195], v[212:215], v[18:33]
	ds_write_b128 v188, v[146:149] offset:18432
	v_mfma_f32_32x32x16_bf16 v[2:17], v[196:199], v[212:215], v[2:17]
	s_waitcnt vmcnt(6)
	ds_write_b128 v188, v[150:153] offset:23040
	v_mfma_f32_32x32x16_bf16 v[114:129], v[216:219], v[234:237], v[114:129]
	s_waitcnt vmcnt(5)
	ds_write_b128 v188, v[154:157] offset:27648
	v_mfma_f32_32x32x16_bf16 v[98:113], v[224:227], v[234:237], v[98:113]
	s_waitcnt vmcnt(4)
	ds_write_b128 v188, v[158:161] offset:32256
	v_mfma_f32_32x32x16_bf16 v[82:97], v[216:219], v[238:241], v[82:97]
	s_waitcnt vmcnt(3)
	ds_write_b128 v188, v[162:165] offset:36864
	v_mfma_f32_32x32x16_bf16 v[66:81], v[224:227], v[238:241], v[66:81]
	s_waitcnt vmcnt(2)
	ds_write_b128 v188, v[166:169] offset:41472
	v_mfma_f32_32x32x16_bf16 v[50:65], v[216:219], v[242:245], v[50:65]
	s_waitcnt vmcnt(1)
	ds_write_b128 v188, v[170:173] offset:46080
	v_mfma_f32_32x32x16_bf16 v[34:49], v[224:227], v[242:245], v[34:49]
	s_waitcnt vmcnt(0)
	ds_write_b128 v188, v[174:177] offset:50688
	v_mfma_f32_32x32x16_bf16 v[18:33], v[216:219], v[246:249], v[18:33]
	v_mfma_f32_32x32x16_bf16 v[2:17], v[224:227], v[246:249], v[2:17]
	s_setprio 0
	s_branch .LBB0_676

; __device__ __forceinline__ void lds_barrier() { asm volatile("s_waitcnt lgkmcnt(0)\n\ts_barrier" ::: "memory"); }
; __device__ __forceinline__ f32x16 mfma32(bf16x8 a, bf16x8 b, f32x16 c) { return __builtin_amdgcn_mfma_f32_32x32x16_bf16(a, b, c, 0, 0, 0); }
; __device__ __forceinline__ void gemm_big(const bf16_t* __restrict__ A, long lda, const bf16_t* __restrict__ Bt, int K, f32x16 (&acc)[2][4], unsigned char* lds) {
;     ...
;     for (int kc = 0; kc < nk; ++kc) {
;         bf16x8 af[2][2], bfr[2][4];
;         af[0][0] = *(const bf16x8*)(Ac); af[0][1] = *(const bf16x8*)(Ac + 32 * GLD);
; #pragma unroll
;         for (int ni = 0; ni < 4; ++ni) bfr[0][ni] = *(const bf16x8*)(Bc + ni * 32 * GLD);
;         __builtin_amdgcn_s_setprio(3);
; #pragma unroll
;         for (int ks = 0; ks < 4; ++ks) {
;             const int cb = ks & 1, nb = cb ^ 1;
;             if (ks < 3) {
;                 af[nb][0] = *(const bf16x8*)(Ac + (ks + 1) * 16); af[nb][1] = *(const bf16x8*)(Ac + 32 * GLD + (ks + 1) * 16);
; #pragma unroll
;                 for (int ni = 0; ni < 4; ++ni) bfr[nb][ni] = *(const bf16x8*)(Bc + ni * 32 * GLD + (ks + 1) * 16);
;             }
;             __builtin_amdgcn_sched_barrier(0);
; #pragma unroll
;             for (int ni = 0; ni < 4; ++ni) { acc[0][ni] = mfma32(af[cb][0], bfr[cb][ni], acc[0][ni]); acc[1][ni] = mfma32(af[cb][1], bfr[cb][ni], acc[1][ni]); }
;             __builtin_amdgcn_sched_barrier(0);
;         }
;         __builtin_amdgcn_s_setprio(0);
;         lds_barrier();
;         if (kc + 1 < nk) {
;             lstore();
;             if (kc + 2 < nk) gload(kc + 2);
;             lds_barrier();
;         }
;     }
.LBB0_775:
	s_cmp_gt_u32 s14, 42
	s_cbranch_scc1 .Lmy_gorig_1
	ds_read_b128 v[190:193], v187
	ds_read_b128 v[194:197], v187 offset:4608
	ds_read_b128 v[198:201], v188 offset:18432
	ds_read_b128 v[202:205], v188 offset:23040
	ds_read_b128 v[206:209], v188 offset:27648
	ds_read_b128 v[210:213], v188 offset:32256
	s_setprio 3
	ds_read_b128 v[214:217], v187 offset:32
	ds_read_b128 v[218:221], v187 offset:4640
	ds_read_b128 v[234:237], v188 offset:18464
	ds_read_b128 v[238:241], v188 offset:23072
	ds_read_b128 v[242:245], v188 offset:27680
	ds_read_b128 v[246:249], v188 offset:32288
	s_waitcnt lgkmcnt(9)
	v_mfma_f32_32x32x16_bf16 v[114:129], v[190:193], v[198:201], v[114:129]
	v_mfma_f32_32x32x16_bf16 v[50:65], v[194:197], v[198:201], v[50:65]
	s_waitcnt lgkmcnt(8)
	v_mfma_f32_32x32x16_bf16 v[98:113], v[190:193], v[202:205], v[98:113]
	v_mfma_f32_32x32x16_bf16 v[34:49], v[194:197], v[202:205], v[34:49]
	s_waitcnt lgkmcnt(7)
	v_mfma_f32_32x32x16_bf16 v[82:97], v[190:193], v[206:209], v[82:97]
	v_mfma_f32_32x32x16_bf16 v[18:33], v[194:197], v[206:209], v[18:33]
	s_waitcnt lgkmcnt(6)
	v_mfma_f32_32x32x16_bf16 v[66:81], v[190:193], v[210:213], v[66:81]
	v_mfma_f32_32x32x16_bf16 v[2:17], v[194:197], v[210:213], v[2:17]
	ds_read_b128 v[190:193], v187 offset:64
	ds_read_b128 v[194:197], v187 offset:4672
	ds_read_b128 v[198:201], v188 offset:18496
	ds_read_b128 v[202:205], v188 offset:23104
	ds_read_b128 v[206:209], v188 offset:27712
	ds_read_b128 v[210:213], v188 offset:32320
	s_waitcnt lgkmcnt(9)
	v_mfma_f32_32x32x16_bf16 v[114:129], v[214:217], v[234:237], v[114:129]
	v_mfma_f32_32x32x16_bf16 v[50:65], v[218:221], v[234:237], v[50:65]
	s_waitcnt lgkmcnt(8)
	v_mfma_f32_32x32x16_bf16 v[98:113], v[214:217], v[238:241], v[98:113]
	v_mfma_f32_32x32x16_bf16 v[34:49], v[218:221], v[238:241], v[34:49]
	s_waitcnt lgkmcnt(7)
	v_mfma_f32_32x32x16_bf16 v[82:97], v[214:217], v[242:245], v[82:97]
	v_mfma_f32_32x32x16_bf16 v[18:33], v[218:221], v[242:245], v[18:33]
	s_waitcnt lgkmcnt(6)
	v_mfma_f32_32x32x16_bf16 v[66:81], v[214:217], v[246:249], v[66:81]
	v_mfma_f32_32x32x16_bf16 v[2:17], v[218:221], v[246:249], v[2:17]
	ds_read_b128 v[214:217], v187 offset:96
	ds_read_b128 v[218:221], v187 offset:4704
	ds_read_b128 v[234:237], v188 offset:18528
	ds_read_b128 v[238:241], v188 offset:23136
	ds_read_b128 v[242:245], v188 offset:27744
	ds_read_b128 v[246:249], v188 offset:32352
	s_waitcnt lgkmcnt(9)
	v_mfma_f32_32x32x16_bf16 v[114:129], v[190:193], v[198:201], v[114:129]
	v_mfma_f32_32x32x16_bf16 v[50:65], v[194:197], v[198:201], v[50:65]
	s_waitcnt lgkmcnt(0)
	s_barrier
	s_cmpk_eq_i32 s4, 0x1500
	s_cbranch_scc1 .Lmy_gB_1
	v_mfma_f32_32x32x16_bf16 v[98:113], v[190:193], v[202:205], v[98:113]
	s_waitcnt vmcnt(9)
	ds_write_b128 v189, v[130:133]
	v_mfma_f32_32x32x16_bf16 v[34:49], v[194:197], v[202:205], v[34:49]
	ds_write_b128 v189, v[134:137] offset:4608
	v_mfma_f32_32x32x16_bf16 v[82:97], v[190:193], v[206:209], v[82:97]
	ds_write_b128 v189, v[138:141] offset:9216
	s_add_u32 vcc_lo, s4, 0x78a8000
	s_addc_u32 vcc_hi, s5, 0
	s_nop 0
	v_lshl_add_u64 v[130:131], v[184:185], 0, vcc
	global_load_dwordx4 v[130:133], v[130:131], off offset:256
	v_mfma_f32_32x32x16_bf16 v[18:33], v[194:197], v[206:209], v[18:33]
	s_waitcnt vmcnt(8)
	ds_write_b128 v189, v[142:145] offset:13824
	s_add_u32 vcc_lo, s4, 0x78d4000
	s_addc_u32 vcc_hi, s5, 0
	s_nop 0
	v_lshl_add_u64 v[134:135], v[184:185], 0, vcc
	global_load_dwordx4 v[134:137], v[134:135], off offset:256
	v_mfma_f32_32x32x16_bf16 v[66:81], v[190:193], v[210:213], v[66:81]
	ds_write_b128 v189, v[146:149] offset:18432
	s_add_u32 vcc_lo, s4, 0x7900000
	s_addc_u32 vcc_hi, s5, 0
	s_nop 0
	v_lshl_add_u64 v[138:139], v[184:185], 0, vcc
	global_load_dwordx4 v[138:141], v[138:139], off offset:256
	v_mfma_f32_32x32x16_bf16 v[2:17], v[194:197], v[210:213], v[2:17]
	s_waitcnt vmcnt(9)
	ds_write_b128 v189, v[150:153] offset:23040
	s_add_u32 vcc_lo, s4, 0x792c000
	s_addc_u32 vcc_hi, s5, 0
	s_nop 0
	v_lshl_add_u64 v[142:143], v[184:185], 0, vcc
	global_load_dwordx4 v[142:145], v[142:143], off offset:256
	v_mfma_f32_32x32x16_bf16 v[114:129], v[214:217], v[234:237], v[114:129]
	s_waitcnt vmcnt(9)
	ds_write_b128 v189, v[154:157] offset:27648
	s_add_u32 vcc_lo, s4, 0xf08000
	s_addc_u32 vcc_hi, s5, 0
	s_nop 0
	v_lshl_add_u64 v[146:147], v[182:183], 0, vcc
	global_load_dwordx4 v[146:149], v[146:147], off offset:256
	v_mfma_f32_32x32x16_bf16 v[50:65], v[218:221], v[234:237], v[50:65]
	s_waitcnt vmcnt(9)
	ds_write_b128 v189, v[158:161] offset:32256
	s_add_u32 vcc_lo, s4, 0xf34000
	s_addc_u32 vcc_hi, s5, 0
	s_nop 0
	v_lshl_add_u64 v[150:151], v[182:183], 0, vcc
	global_load_dwordx4 v[150:153], v[150:151], off offset:256
	v_mfma_f32_32x32x16_bf16 v[98:113], v[214:217], v[238:241], v[98:113]
	s_waitcnt vmcnt(9)
	ds_write_b128 v189, v[162:165] offset:36864
	s_add_u32 vcc_lo, s4, 0xf60000
	s_addc_u32 vcc_hi, s5, 0
	s_nop 0
	v_lshl_add_u64 v[154:155], v[182:183], 0, vcc
	global_load_dwordx4 v[154:157], v[154:155], off offset:256
	v_mfma_f32_32x32x16_bf16 v[34:49], v[218:221], v[238:241], v[34:49]
	s_waitcnt vmcnt(9)
	ds_write_b128 v189, v[166:169] offset:41472
	s_add_u32 vcc_lo, s4, 0xf8c000
	s_addc_u32 vcc_hi, s5, 0
	s_nop 0
	v_lshl_add_u64 v[158:159], v[182:183], 0, vcc
	global_load_dwordx4 v[158:161], v[158:159], off offset:256
	v_mfma_f32_32x32x16_bf16 v[82:97], v[214:217], v[242:245], v[82:97]
	s_waitcnt vmcnt(9)
	ds_write_b128 v189, v[170:173] offset:46080
	s_add_u32 vcc_lo, s4, 0xfb8000
	s_addc_u32 vcc_hi, s5, 0
	s_nop 0
	v_lshl_add_u64 v[162:163], v[182:183], 0, vcc
	global_load_dwordx4 v[162:165], v[162:163], off offset:256
	v_mfma_f32_32x32x16_bf16 v[18:33], v[218:221], v[242:245], v[18:33]
	s_waitcnt vmcnt(9)
	ds_write_b128 v189, v[174:177] offset:50688
	s_add_u32 vcc_lo, s4, 0xfe4000
	s_addc_u32 vcc_hi, s5, 0
	s_nop 0
	v_lshl_add_u64 v[166:167], v[182:183], 0, vcc
	global_load_dwordx4 v[166:169], v[166:167], off offset:256
	v_mfma_f32_32x32x16_bf16 v[66:81], v[214:217], v[246:249], v[66:81]
	s_add_u32 vcc_lo, s4, 0x1010000
	s_addc_u32 vcc_hi, s5, 0
	s_nop 0
	v_lshl_add_u64 v[170:171], v[182:183], 0, vcc
	global_load_dwordx4 v[170:173], v[170:171], off offset:256
	v_mfma_f32_32x32x16_bf16 v[2:17], v[218:221], v[246:249], v[2:17]
	s_add_u32 vcc_lo, s4, 0x103c000
	s_addc_u32 vcc_hi, s5, 0
	s_nop 0
	v_lshl_add_u64 v[174:175], v[182:183], 0, vcc
	global_load_dwordx4 v[174:177], v[174:175], off offset:256
	s_setprio 0
	s_branch .LBB0_773
; __device__ __forceinline__ void lds_barrier() { asm volatile("s_waitcnt lgkmcnt(0)\n\ts_barrier" ::: "memory"); }
; __device__ __forceinline__ f32x16 mfma32(bf16x8 a, bf16x8 b, f32x16 c) { return __builtin_amdgcn_mfma_f32_32x32x16_bf16(a, b, c, 0, 0, 0); }
; __device__ __forceinline__ void gemm_big(const bf16_t* __restrict__ A, long lda, const bf16_t* __restrict__ Bt, int K, f32x16 (&acc)[2][4], unsigned char* lds) {
;     ...
;         for (int ks = 0; ks < 4; ++ks) {
;             const int cb = ks & 1, nb = cb ^ 1;
;             if (ks < 3) {
;                 af[nb][0] = *(const bf16x8*)(Ac + (ks + 1) * 16); af[nb][1] = *(const bf16x8*)(Ac + 32 * GLD + (ks + 1) * 16);
; #pragma unroll
;                 for (int ni = 0; ni < 4; ++ni) bfr[nb][ni] = *(const bf16x8*)(Bc + ni * 32 * GLD + (ks + 1) * 16);
;             }
;             __builtin_amdgcn_sched_barrier(0);
; #pragma unroll
;             for (int ni = 0; ni < 4; ++ni) { acc[0][ni] = mfma32(af[cb][0], bfr[cb][ni], acc[0][ni]); acc[1][ni] = mfma32(af[cb][1], bfr[cb][ni], acc[1][ni]); }
;             __builtin_amdgcn_sched_barrier(0);
;         }
;         __builtin_amdgcn_s_setprio(0);
;         lds_barrier();
;         if (kc + 1 < nk) {
;             lstore();
;             if (kc + 2 < nk) gload(kc + 2);
;             lds_barrier();
;         }
.Lmy_gB_1:
	v_mfma_f32_32x32x16_bf16 v[98:113], v[190:193], v[202:205], v[98:113]
	s_waitcnt vmcnt(9)
	ds_write_b128 v189, v[130:133]
	v_mfma_f32_32x32x16_bf16 v[34:49], v[194:197], v[202:205], v[34:49]
	ds_write_b128 v189, v[134:137] offset:4608
	v_mfma_f32_32x32x16_bf16 v[82:97], v[190:193], v[206:209], v[82:97]
	ds_write_b128 v189, v[138:141] offset:9216
	v_mfma_f32_32x32x16_bf16 v[18:33], v[194:197], v[206:209], v[18:33]
	s_waitcnt vmcnt(7)
	ds_write_b128 v189, v[142:145] offset:13824
	v_mfma_f32_32x32x16_bf16 v[66:81], v[190:193], v[210:213], v[66:81]
	ds_write_b128 v189, v[146:149] offset:18432
	v_mfma_f32_32x32x16_bf16 v[2:17], v[194:197], v[210:213], v[2:17]
	s_waitcnt vmcnt(6)
	ds_write_b128 v189, v[150:153] offset:23040
	v_mfma_f32_32x32x16_bf16 v[114:129], v[214:217], v[234:237], v[114:129]
	s_waitcnt vmcnt(5)
	ds_write_b128 v189, v[154:157] offset:27648
	v_mfma_f32_32x32x16_bf16 v[50:65], v[218:221], v[234:237], v[50:65]
	s_waitcnt vmcnt(4)
	ds_write_b128 v189, v[158:161] offset:32256
	v_mfma_f32_32x32x16_bf16 v[98:113], v[214:217], v[238:241], v[98:113]
	s_waitcnt vmcnt(3)
	ds_write_b128 v189, v[162:165] offset:36864
	v_mfma_f32_32x32x16_bf16 v[34:49], v[218:221], v[238:241], v[34:49]
	s_waitcnt vmcnt(2)
	ds_write_b128 v189, v[166:169] offset:41472
	v_mfma_f32_32x32x16_bf16 v[82:97], v[214:217], v[242:245], v[82:97]
	s_waitcnt vmcnt(1)
	ds_write_b128 v189, v[170:173] offset:46080
	v_mfma_f32_32x32x16_bf16 v[18:33], v[218:221], v[242:245], v[18:33]
	s_waitcnt vmcnt(0)
	ds_write_b128 v189, v[174:177] offset:50688
	v_mfma_f32_32x32x16_bf16 v[66:81], v[214:217], v[246:249], v[66:81]
	v_mfma_f32_32x32x16_bf16 v[2:17], v[218:221], v[246:249], v[2:17]
	s_setprio 0
	s_branch .LBB0_773

; __device__ __forceinline__ void lds_barrier() { asm volatile("s_waitcnt lgkmcnt(0)\n\ts_barrier" ::: "memory"); }
; __device__ __forceinline__ f32x16 mfma32(bf16x8 a, bf16x8 b, f32x16 c) { return __builtin_amdgcn_mfma_f32_32x32x16_bf16(a, b, c, 0, 0, 0); }
; __device__ __forceinline__ void gemm_big(const bf16_t* __restrict__ A, long lda, const bf16_t* __restrict__ Bt, int K, f32x16 (&acc)[2][4], unsigned char* lds) {
;     ...
;     for (int kc = 0; kc < nk; ++kc) {
;         bf16x8 af[2][2], bfr[2][4];
;         af[0][0] = *(const bf16x8*)(Ac); af[0][1] = *(const bf16x8*)(Ac + 32 * GLD);
; #pragma unroll
;         for (int ni = 0; ni < 4; ++ni) bfr[0][ni] = *(const bf16x8*)(Bc + ni * 32 * GLD);
;         __builtin_amdgcn_s_setprio(3);
; #pragma unroll
;         for (int ks = 0; ks < 4; ++ks) {
;             const int cb = ks & 1, nb = cb ^ 1;
;             if (ks < 3) {
;                 af[nb][0] = *(const bf16x8*)(Ac + (ks + 1) * 16); af[nb][1] = *(const bf16x8*)(Ac + 32 * GLD + (ks + 1) * 16);
; #pragma unroll
;                 for (int ni = 0; ni < 4; ++ni) bfr[nb][ni] = *(const bf16x8*)(Bc + ni * 32 * GLD + (ks + 1) * 16);
;             }
;             __builtin_amdgcn_sched_barrier(0);
; #pragma unroll
;             for (int ni = 0; ni < 4; ++ni) { acc[0][ni] = mfma32(af[cb][0], bfr[cb][ni], acc[0][ni]); acc[1][ni] = mfma32(af[cb][1], bfr[cb][ni], acc[1][ni]); }
;             __builtin_amdgcn_sched_barrier(0);
;         }
;         __builtin_amdgcn_s_setprio(0);
;         lds_barrier();
;         if (kc + 1 < nk) {
;             lstore();
;             if (kc + 2 < nk) gload(kc + 2);
;             lds_barrier();
;         }
;     }
.LBB0_788:
	s_cmp_gt_u32 s5, 14
	s_cbranch_scc1 .Lmy_gorig_0
	ds_read_b128 v[190:193], v188
	ds_read_b128 v[194:197], v188 offset:4608
	ds_read_b128 v[198:201], v189 offset:18432
	ds_read_b128 v[202:205], v189 offset:23040
	ds_read_b128 v[206:209], v189 offset:27648
	ds_read_b128 v[210:213], v189 offset:32256
	s_setprio 3
	ds_read_b128 v[214:217], v188 offset:32
	ds_read_b128 v[234:237], v188 offset:4640
	ds_read_b128 v[238:241], v189 offset:18464
	ds_read_b128 v[242:245], v189 offset:23072
	ds_read_b128 v[246:249], v189 offset:27680
	ds_read_b128 v[218:221], v189 offset:32288
	s_waitcnt lgkmcnt(9)
	v_mfma_f32_32x32x16_bf16 v[114:129], v[190:193], v[198:201], v[114:129]
	v_mfma_f32_32x32x16_bf16 v[82:97], v[194:197], v[198:201], v[82:97]
	s_waitcnt lgkmcnt(8)
	v_mfma_f32_32x32x16_bf16 v[98:113], v[190:193], v[202:205], v[98:113]
	v_mfma_f32_32x32x16_bf16 v[66:81], v[194:197], v[202:205], v[66:81]
	s_waitcnt lgkmcnt(7)
	v_mfma_f32_32x32x16_bf16 v[50:65], v[190:193], v[206:209], v[50:65]
	v_mfma_f32_32x32x16_bf16 v[18:33], v[194:197], v[206:209], v[18:33]
	s_waitcnt lgkmcnt(6)
	v_mfma_f32_32x32x16_bf16 v[34:49], v[190:193], v[210:213], v[34:49]
	v_mfma_f32_32x32x16_bf16 v[2:17], v[194:197], v[210:213], v[2:17]
	ds_read_b128 v[190:193], v188 offset:64
	ds_read_b128 v[194:197], v188 offset:4672
	ds_read_b128 v[198:201], v189 offset:18496
	ds_read_b128 v[202:205], v189 offset:23104
	ds_read_b128 v[206:209], v189 offset:27712
	ds_read_b128 v[210:213], v189 offset:32320
	s_waitcnt lgkmcnt(9)
	v_mfma_f32_32x32x16_bf16 v[114:129], v[214:217], v[238:241], v[114:129]
	v_mfma_f32_32x32x16_bf16 v[82:97], v[234:237], v[238:241], v[82:97]
	s_waitcnt lgkmcnt(8)
	v_mfma_f32_32x32x16_bf16 v[98:113], v[214:217], v[242:245], v[98:113]
	v_mfma_f32_32x32x16_bf16 v[66:81], v[234:237], v[242:245], v[66:81]
	s_waitcnt lgkmcnt(7)
	v_mfma_f32_32x32x16_bf16 v[50:65], v[214:217], v[246:249], v[50:65]
	v_mfma_f32_32x32x16_bf16 v[18:33], v[234:237], v[246:249], v[18:33]
	s_waitcnt lgkmcnt(6)
	v_mfma_f32_32x32x16_bf16 v[34:49], v[214:217], v[218:221], v[34:49]
	v_mfma_f32_32x32x16_bf16 v[2:17], v[234:237], v[218:221], v[2:17]
	ds_read_b128 v[214:217], v188 offset:96
	ds_read_b128 v[218:221], v188 offset:4704
	ds_read_b128 v[234:237], v189 offset:18528
	ds_read_b128 v[238:241], v189 offset:23136
	ds_read_b128 v[242:245], v189 offset:27744
	ds_read_b128 v[246:249], v189 offset:32352
	s_waitcnt lgkmcnt(9)
	v_mfma_f32_32x32x16_bf16 v[114:129], v[190:193], v[198:201], v[114:129]
	v_mfma_f32_32x32x16_bf16 v[82:97], v[194:197], v[198:201], v[82:97]
	s_waitcnt lgkmcnt(0)
	s_barrier
	s_cmpk_eq_i32 s6, 0x700
	s_cbranch_scc1 .Lmy_gB_0
	v_mfma_f32_32x32x16_bf16 v[98:113], v[190:193], v[202:205], v[98:113]
	s_waitcnt vmcnt(9)
	ds_write_b128 v187, v[130:133]
	v_mfma_f32_32x32x16_bf16 v[66:81], v[194:197], v[202:205], v[66:81]
	ds_write_b128 v187, v[134:137] offset:4608
	v_mfma_f32_32x32x16_bf16 v[50:65], v[190:193], v[206:209], v[50:65]
	ds_write_b128 v187, v[138:141] offset:9216
	s_add_u32 vcc_lo, s6, 0x38a8000
	s_addc_u32 vcc_hi, s7, 0
	s_nop 0
	v_lshl_add_u64 v[130:131], v[184:185], 0, vcc
	global_load_dwordx4 v[130:133], v[130:131], off offset:256
	v_mfma_f32_32x32x16_bf16 v[18:33], v[194:197], v[206:209], v[18:33]
	s_waitcnt vmcnt(8)
	ds_write_b128 v187, v[142:145] offset:13824
	s_add_u32 vcc_lo, s6, 0x38b8000
	s_addc_u32 vcc_hi, s7, 0
	s_nop 0
	v_lshl_add_u64 v[134:135], v[184:185], 0, vcc
	global_load_dwordx4 v[134:137], v[134:135], off offset:256
	v_mfma_f32_32x32x16_bf16 v[34:49], v[190:193], v[210:213], v[34:49]
	ds_write_b128 v187, v[146:149] offset:18432
	s_add_u32 vcc_lo, s6, 0x38c8000
	s_addc_u32 vcc_hi, s7, 0
	s_nop 0
	v_lshl_add_u64 v[138:139], v[184:185], 0, vcc
	global_load_dwordx4 v[138:141], v[138:139], off offset:256
	v_mfma_f32_32x32x16_bf16 v[2:17], v[194:197], v[210:213], v[2:17]
	s_waitcnt vmcnt(9)
	ds_write_b128 v187, v[150:153] offset:23040
	s_add_u32 vcc_lo, s6, 0x38d8000
	s_addc_u32 vcc_hi, s7, 0
	s_nop 0
	v_lshl_add_u64 v[142:143], v[184:185], 0, vcc
	global_load_dwordx4 v[142:145], v[142:143], off offset:256
	v_mfma_f32_32x32x16_bf16 v[114:129], v[214:217], v[234:237], v[114:129]
	s_waitcnt vmcnt(9)
	ds_write_b128 v187, v[154:157] offset:27648
	s_add_u32 vcc_lo, s6, 0x408000
	s_addc_u32 vcc_hi, s7, 0
	s_nop 0
	v_lshl_add_u64 v[146:147], v[182:183], 0, vcc
	global_load_dwordx4 v[146:149], v[146:147], off offset:256
	v_mfma_f32_32x32x16_bf16 v[82:97], v[218:221], v[234:237], v[82:97]
	s_waitcnt vmcnt(9)
	ds_write_b128 v187, v[158:161] offset:32256
	s_add_u32 vcc_lo, s6, 0x418000
	s_addc_u32 vcc_hi, s7, 0
	s_nop 0
	v_lshl_add_u64 v[150:151], v[182:183], 0, vcc
	global_load_dwordx4 v[150:153], v[150:151], off offset:256
	v_mfma_f32_32x32x16_bf16 v[98:113], v[214:217], v[238:241], v[98:113]
	s_waitcnt vmcnt(9)
	ds_write_b128 v187, v[162:165] offset:36864
	s_add_u32 vcc_lo, s6, 0x428000
	s_addc_u32 vcc_hi, s7, 0
	s_nop 0
	v_lshl_add_u64 v[154:155], v[182:183], 0, vcc
	global_load_dwordx4 v[154:157], v[154:155], off offset:256
	v_mfma_f32_32x32x16_bf16 v[66:81], v[218:221], v[238:241], v[66:81]
	s_waitcnt vmcnt(9)
	ds_write_b128 v187, v[166:169] offset:41472
	s_add_u32 vcc_lo, s6, 0x438000
	s_addc_u32 vcc_hi, s7, 0
	s_nop 0
	v_lshl_add_u64 v[158:159], v[182:183], 0, vcc
	global_load_dwordx4 v[158:161], v[158:159], off offset:256
	v_mfma_f32_32x32x16_bf16 v[50:65], v[214:217], v[242:245], v[50:65]
	s_waitcnt vmcnt(9)
	ds_write_b128 v187, v[170:173] offset:46080
	s_add_u32 vcc_lo, s6, 0x448000
	s_addc_u32 vcc_hi, s7, 0
	s_nop 0
	v_lshl_add_u64 v[162:163], v[182:183], 0, vcc
	global_load_dwordx4 v[162:165], v[162:163], off offset:256
	v_mfma_f32_32x32x16_bf16 v[18:33], v[218:221], v[242:245], v[18:33]
	s_waitcnt vmcnt(9)
	ds_write_b128 v187, v[174:177] offset:50688
	s_add_u32 vcc_lo, s6, 0x458000
	s_addc_u32 vcc_hi, s7, 0
	s_nop 0
	v_lshl_add_u64 v[166:167], v[182:183], 0, vcc
	global_load_dwordx4 v[166:169], v[166:167], off offset:256
	v_mfma_f32_32x32x16_bf16 v[34:49], v[214:217], v[246:249], v[34:49]
	s_add_u32 vcc_lo, s6, 0x468000
	s_addc_u32 vcc_hi, s7, 0
	s_nop 0
	v_lshl_add_u64 v[170:171], v[182:183], 0, vcc
	global_load_dwordx4 v[170:173], v[170:171], off offset:256
	v_mfma_f32_32x32x16_bf16 v[2:17], v[218:221], v[246:249], v[2:17]
	s_add_u32 vcc_lo, s6, 0x478000
	s_addc_u32 vcc_hi, s7, 0
	s_nop 0
	v_lshl_add_u64 v[174:175], v[182:183], 0, vcc
	global_load_dwordx4 v[174:177], v[174:175], off offset:256
	s_setprio 0
	s_branch .LBB0_786
; __device__ __forceinline__ void lds_barrier() { asm volatile("s_waitcnt lgkmcnt(0)\n\ts_barrier" ::: "memory"); }
; __device__ __forceinline__ f32x16 mfma32(bf16x8 a, bf16x8 b, f32x16 c) { return __builtin_amdgcn_mfma_f32_32x32x16_bf16(a, b, c, 0, 0, 0); }
; __device__ __forceinline__ void gemm_big(const bf16_t* __restrict__ A, long lda, const bf16_t* __restrict__ Bt, int K, f32x16 (&acc)[2][4], unsigned char* lds) {
;     ...
;         for (int ks = 0; ks < 4; ++ks) {
;             const int cb = ks & 1, nb = cb ^ 1;
;             if (ks < 3) {
;                 af[nb][0] = *(const bf16x8*)(Ac + (ks + 1) * 16); af[nb][1] = *(const bf16x8*)(Ac + 32 * GLD + (ks + 1) * 16);
; #pragma unroll
;                 for (int ni = 0; ni < 4; ++ni) bfr[nb][ni] = *(const bf16x8*)(Bc + ni * 32 * GLD + (ks + 1) * 16);
;             }
;             __builtin_amdgcn_sched_barrier(0);
; #pragma unroll
;             for (int ni = 0; ni < 4; ++ni) { acc[0][ni] = mfma32(af[cb][0], bfr[cb][ni], acc[0][ni]); acc[1][ni] = mfma32(af[cb][1], bfr[cb][ni], acc[1][ni]); }
;             __builtin_amdgcn_sched_barrier(0);
;         }
;         __builtin_amdgcn_s_setprio(0);
;         lds_barrier();
;         if (kc + 1 < nk) {
;             lstore();
;             if (kc + 2 < nk) gload(kc + 2);
;             lds_barrier();
;         }
.Lmy_gB_0:
	v_mfma_f32_32x32x16_bf16 v[98:113], v[190:193], v[202:205], v[98:113]
	s_waitcnt vmcnt(9)
	ds_write_b128 v187, v[130:133]
	v_mfma_f32_32x32x16_bf16 v[66:81], v[194:197], v[202:205], v[66:81]
	ds_write_b128 v187, v[134:137] offset:4608
	v_mfma_f32_32x32x16_bf16 v[50:65], v[190:193], v[206:209], v[50:65]
	ds_write_b128 v187, v[138:141] offset:9216
	v_mfma_f32_32x32x16_bf16 v[18:33], v[194:197], v[206:209], v[18:33]
	s_waitcnt vmcnt(7)
	ds_write_b128 v187, v[142:145] offset:13824
	v_mfma_f32_32x32x16_bf16 v[34:49], v[190:193], v[210:213], v[34:49]
	ds_write_b128 v187, v[146:149] offset:18432
	v_mfma_f32_32x32x16_bf16 v[2:17], v[194:197], v[210:213], v[2:17]
	s_waitcnt vmcnt(6)
	ds_write_b128 v187, v[150:153] offset:23040
	v_mfma_f32_32x32x16_bf16 v[114:129], v[214:217], v[234:237], v[114:129]
	s_waitcnt vmcnt(5)
	ds_write_b128 v187, v[154:157] offset:27648
	v_mfma_f32_32x32x16_bf16 v[82:97], v[218:221], v[234:237], v[82:97]
	s_waitcnt vmcnt(4)
	ds_write_b128 v187, v[158:161] offset:32256
	v_mfma_f32_32x32x16_bf16 v[98:113], v[214:217], v[238:241], v[98:113]
	s_waitcnt vmcnt(3)
	ds_write_b128 v187, v[162:165] offset:36864
	v_mfma_f32_32x32x16_bf16 v[66:81], v[218:221], v[238:241], v[66:81]
	s_waitcnt vmcnt(2)
	ds_write_b128 v187, v[166:169] offset:41472
	v_mfma_f32_32x32x16_bf16 v[50:65], v[214:217], v[242:245], v[50:65]
	s_waitcnt vmcnt(1)
	ds_write_b128 v187, v[170:173] offset:46080
	v_mfma_f32_32x32x16_bf16 v[18:33], v[218:221], v[242:245], v[18:33]
	s_waitcnt vmcnt(0)
	ds_write_b128 v187, v[174:177] offset:50688
	v_mfma_f32_32x32x16_bf16 v[34:49], v[214:217], v[246:249], v[34:49]
	v_mfma_f32_32x32x16_bf16 v[2:17], v[218:221], v[246:249], v[2:17]
	s_setprio 0
	s_branch .LBB0_786
